# EpiGU8: ssq row loads issued ahead of the tile's final 32 MFMAs (fresh regs), barrier wait vmcnt(8); stacked on XCD-barrier downgrade + q-prep hoist
# baseline (speedup 1.0000x reference)
; #define MFMA16(a, b, c) __builtin_amdgcn_mfma_f32_16x16x32_bf16((a), (b), (c), 0, 0, 0)
; template <class Epi>
; DI void gemm8_tile(const bf16_t* __restrict__ Ab, int lda, const bf16_t* __restrict__ Bb, int ldb, int K, int brow, int bcol, const Epi epi,
;                    bool staged, bool has_next, const bf16_t* __restrict__ Abn, const bf16_t* __restrict__ Bbn) {
;     ...
;         for (int n = 0; n < 4; ++n) acc[m][n] = MFMA16(At[m], Bf[n], acc[m][n]);
;       __builtin_amdgcn_sched_barrier(0);
;     }
;     asm volatile("s_waitcnt vmcnt(0)" ::: "memory");
;     __syncthreads();
;   }
;     ...
;   epi.run8(acc, brow + wr * 128, bcol + wc * 64, fr, fq);
;   if (Epi::LDS_SCRATCH) __syncthreads();
;   DI void run8(f32x4 (&acc)[8][4], int rb, int cb, int fr, int fq) const {
;     ...
;     for (int m = 0; m < 8; ++m)
; #pragma unroll
;       for (int j = 0; j < 4; ++j) rsv[m][j] = rsqrtf(ssq[rb + m * 16 + fq * 4 + j] * (1.f / D) + EPS);
.LBB0_456:
	s_waitcnt lgkmcnt(0)
	v_lshrrev_b32_e32 v250, 4, v228
	v_add_u32_e32 v248, s3, v230
	v_lshl_or_b32 v248, v250, 2, v248
	v_ashrrev_i32_e32 v249, 31, v248
	v_lshl_add_u64 v[248:249], v[248:249], 2, s[4:5]
	global_load_dwordx4 v[212:215], v[248:249], off
	global_load_dwordx4 v[224:227], v[248:249], off offset:64
	global_load_dwordx4 v[232:235], v[248:249], off offset:128
	global_load_dwordx4 v[236:239], v[248:249], off offset:192
	global_load_dwordx4 v[240:243], v[248:249], off offset:256
	global_load_dwordx4 v[244:247], v[248:249], off offset:320
	v_mfma_f32_16x16x32_bf16 v[122:125], v[58:61], v[2:5], v[126:129]
	v_mfma_f32_16x16x32_bf16 v[126:129], v[58:61], v[138:141], v[146:149]
	v_mfma_f32_16x16x32_bf16 v[114:117], v[58:61], v[142:145], v[118:121]
	v_mfma_f32_16x16x32_bf16 v[118:121], v[58:61], v[202:205], v[150:153]
	v_mfma_f32_16x16x32_bf16 v[106:109], v[50:53], v[2:5], v[110:113]
	v_mfma_f32_16x16x32_bf16 v[110:113], v[50:53], v[138:141], v[154:157]
	v_mfma_f32_16x16x32_bf16 v[98:101], v[50:53], v[142:145], v[102:105]
	v_mfma_f32_16x16x32_bf16 v[102:105], v[50:53], v[202:205], v[158:161]
	v_mfma_f32_16x16x32_bf16 v[90:93], v[42:45], v[2:5], v[94:97]
	v_mfma_f32_16x16x32_bf16 v[94:97], v[42:45], v[138:141], v[162:165]
	v_mfma_f32_16x16x32_bf16 v[82:85], v[42:45], v[142:145], v[86:89]
	v_mfma_f32_16x16x32_bf16 v[86:89], v[42:45], v[202:205], v[166:169]
	v_mfma_f32_16x16x32_bf16 v[74:77], v[34:37], v[2:5], v[78:81]
	v_mfma_f32_16x16x32_bf16 v[78:81], v[34:37], v[138:141], v[170:173]
	v_mfma_f32_16x16x32_bf16 v[66:69], v[34:37], v[142:145], v[70:73]
	v_mfma_f32_16x16x32_bf16 v[70:73], v[34:37], v[202:205], v[174:177]
	global_load_dwordx4 v[170:173], v[248:249], off offset:384
	global_load_dwordx4 v[174:177], v[248:249], off offset:448
	v_mfma_f32_16x16x32_bf16 v[58:61], v[26:29], v[2:5], v[62:65]
	v_mfma_f32_16x16x32_bf16 v[62:65], v[26:29], v[138:141], v[178:181]
	v_mfma_f32_16x16x32_bf16 v[50:53], v[26:29], v[142:145], v[54:57]
	v_mfma_f32_16x16x32_bf16 v[54:57], v[26:29], v[202:205], v[182:185]
	v_mfma_f32_16x16x32_bf16 v[42:45], v[18:21], v[2:5], v[46:49]
	v_mfma_f32_16x16x32_bf16 v[46:49], v[18:21], v[138:141], v[186:189]
	v_mfma_f32_16x16x32_bf16 v[34:37], v[18:21], v[142:145], v[38:41]
	v_mfma_f32_16x16x32_bf16 v[38:41], v[18:21], v[202:205], v[190:193]
	v_mfma_f32_16x16x32_bf16 v[26:29], v[10:13], v[2:5], v[30:33]
	v_mfma_f32_16x16x32_bf16 v[30:33], v[10:13], v[138:141], v[194:197]
	v_mfma_f32_16x16x32_bf16 v[18:21], v[10:13], v[142:145], v[22:25]
	v_mfma_f32_16x16x32_bf16 v[22:25], v[10:13], v[202:205], v[198:201]
	v_mfma_f32_16x16x32_bf16 v[10:13], v[206:209], v[2:5], v[14:17]
	v_mfma_f32_16x16x32_bf16 v[14:17], v[206:209], v[138:141], v[130:133]
	v_mfma_f32_16x16x32_bf16 v[2:5], v[206:209], v[142:145], v[6:9]
	v_mfma_f32_16x16x32_bf16 v[6:9], v[206:209], v[202:205], v[134:137]
	v_lshrrev_b32_e32 v168, 4, v228
	v_add_u32_e32 v130, s3, v230
	v_lshl_or_b32 v131, v229, 6, s31
	v_or_b32_e32 v0, v130, v222
	v_lshl_or_b32 v130, v168, 2, v130
	v_ashrrev_i32_e32 v134, 1, v131
	v_ashrrev_i32_e32 v131, 31, v130
	v_lshl_add_u64 v[130:131], v[130:131], 2, s[4:5]
	s_waitcnt vmcnt(8)
	s_waitcnt vmcnt(8)
	s_barrier
	s_mov_b32 s0, 0x358637bd
	v_mov_b64_e32 v[136:137], s[0:1]
	v_ashrrev_i32_e32 v135, 31, v134
	s_waitcnt vmcnt(7)
	v_pk_fma_f32 v[132:133], v[212:213], s[86:87], v[136:137] op_sel_hi:[1,0,0]
	v_rsq_f32_e32 v167, v132
	s_nop 0
	v_mul_f32_e32 v122, v122, v167
	v_mul_f32_e32 v126, v126, v167
	v_mul_f32_e32 v114, v114, v167
	v_rsq_f32_e32 v166, v133
	v_pk_fma_f32 v[132:133], v[214:215], s[86:87], v[136:137] op_sel_hi:[1,0,0]
	v_mul_f32_e32 v118, v118, v167
	v_rsq_f32_e32 v165, v132
	v_rsq_f32_e32 v163, v133
	s_waitcnt vmcnt(6)
	v_pk_fma_f32 v[132:133], v[224:225], s[86:87], v[136:137] op_sel_hi:[1,0,0]
	v_rsq_f32_e32 v164, v132
	v_rsq_f32_e32 v162, v133
	v_pk_fma_f32 v[132:133], v[226:227], s[86:87], v[136:137] op_sel_hi:[1,0,0]
	v_rsq_f32_e32 v161, v132
	v_rsq_f32_e32 v159, v133
	s_waitcnt vmcnt(5)
	v_pk_fma_f32 v[132:133], v[232:233], s[86:87], v[136:137] op_sel_hi:[1,0,0]
	v_rsq_f32_e32 v160, v132
	v_rsq_f32_e32 v158, v133
	v_pk_fma_f32 v[132:133], v[234:235], s[86:87], v[136:137] op_sel_hi:[1,0,0]
	v_rsq_f32_e32 v157, v132
	v_rsq_f32_e32 v155, v133
	s_waitcnt vmcnt(4)
	v_pk_fma_f32 v[132:133], v[236:237], s[86:87], v[136:137] op_sel_hi:[1,0,0]
	v_rsq_f32_e32 v156, v132
	v_rsq_f32_e32 v154, v133
	v_pk_fma_f32 v[132:133], v[238:239], s[86:87], v[136:137] op_sel_hi:[1,0,0]
	v_rsq_f32_e32 v153, v132
	v_rsq_f32_e32 v150, v133
	s_waitcnt vmcnt(3)
	v_pk_fma_f32 v[132:133], v[240:241], s[86:87], v[136:137] op_sel_hi:[1,0,0]
	v_rsq_f32_e32 v151, v132
	v_rsq_f32_e32 v148, v133
	v_pk_fma_f32 v[132:133], v[242:243], s[86:87], v[136:137] op_sel_hi:[1,0,0]
	v_rsq_f32_e32 v146, v132
	v_rsq_f32_e32 v143, v133
	s_waitcnt vmcnt(2)
	v_pk_fma_f32 v[132:133], v[244:245], s[86:87], v[136:137] op_sel_hi:[1,0,0]
	v_rsq_f32_e32 v145, v132
	v_rsq_f32_e32 v142, v133
	v_pk_fma_f32 v[132:133], v[246:247], s[86:87], v[136:137] op_sel_hi:[1,0,0]
	v_rsq_f32_e32 v140, v132
	v_rsq_f32_e32 v138, v133
	s_waitcnt vmcnt(1)
	v_pk_fma_f32 v[132:133], v[170:171], s[86:87], v[136:137] op_sel_hi:[1,0,0]
	v_rsq_f32_e32 v147, v132
	v_rsq_f32_e32 v144, v133
	v_pk_fma_f32 v[132:133], v[172:173], s[86:87], v[136:137] op_sel_hi:[1,0,0]
	v_rsq_f32_e32 v141, v132
	v_rsq_f32_e32 v139, v133
	s_waitcnt vmcnt(0)
; DI bf16_t to_bf16(float x) { return (bf16_t)(pack_bf16(x, 0.f) & 0xffffu); }
;   DI void run8(f32x4 (&acc)[8][4], int rb, int cb, int fr, int fq) const {
;     const int lane = fq * 16 + fr, wid = (int)(threadIdx.x >> 6);
;     bf16_t* scr = (bf16_t*)(smem + G8_STAGE_B + wid * 1280);
;     const int srow = lane >> 2, sch = lane & 3;
;     bf16_t* ap = act + (size_t)(rb + srow) * LDA + (cb >> 1) + sch * 8;
;     float rsv[8][4];
; #pragma unroll
;     for (int m = 0; m < 8; ++m)
; #pragma unroll
;       for (int j = 0; j < 4; ++j) rsv[m][j] = rsqrtf(ssq[rb + m * 16 + fq * 4 + j] * (1.f / D) + EPS);
; #pragma unroll
;     for (int m = 0; m < 8; ++m) {
; #pragma unroll
;       for (int j = 0; j < 4; ++j)
; #pragma unroll
;         for (int pi = 0; pi < 2; ++pi) {
;           const float g = acc[m][2 * pi][j] * rsv[m][j], u = acc[m][2 * pi + 1][j] * rsv[m][j];
;           const float a = g * __builtin_amdgcn_rcpf(1.f + __expf(-g)) * u;
;           scr[(fq * 4 + j) * 40 + pi * 16 + fr] = to_bf16(a);
;         }
;       __builtin_amdgcn_sched_barrier(0);
;       const u32x4 o = *(const u32x4*)(scr + srow * 40 + sch * 8);
;       *(u32x4*)(ap + (size_t)(m * 16) * LDA) = o;
;       __builtin_amdgcn_sched_barrier(0);
	v_pk_fma_f32 v[130:131], v[174:175], s[86:87], v[136:137] op_sel_hi:[1,0,0]
	v_rsq_f32_e32 v152, v130
	v_rsq_f32_e32 v149, v131
	v_pk_fma_f32 v[130:131], v[176:177], s[86:87], v[136:137] op_sel_hi:[1,0,0]
	v_rsq_f32_e32 v136, v130
	s_movk_i32 s0, 0x1680
	v_lshlrev_b32_e32 v132, 1, v223
	v_rsq_f32_e32 v133, v131
	v_mov_b64_e32 v[130:131], s[52:53]
	v_mad_i64_i32 v[130:131], s[0:1], v0, s0, v[130:131]
	v_lshlrev_b32_e32 v0, 4, v223
	v_lshl_add_u64 v[130:131], v[134:135], 1, v[130:131]
	v_and_b32_e32 v0, 48, v0
	v_mul_u32_u24_e32 v134, 0x50, v222
	v_lshl_add_u64 v[130:131], v[130:131], 0, v[0:1]
	v_add3_u32 v0, v217, v134, v0
	v_mul_u32_u24_e32 v134, 0x140, v168
	v_add3_u32 v132, v217, v132, v134
	v_mul_f32_e32 v134, 0xbfb8aa3b, v122
	v_exp_f32_e32 v134, v134
	s_nop 0
	v_add_f32_e32 v134, 1.0, v134
	v_rcp_f32_e32 v134, v134
	s_nop 0
	v_mul_f32_e32 v122, v122, v134
	v_mul_f32_e32 v122, v126, v122
	v_cvt_pk_bf16_f32 v122, v122, s0
	ds_write_b16 v132, v122
	v_mul_f32_e32 v122, 0xbfb8aa3b, v114
	v_exp_f32_e32 v122, v122
	s_nop 0
	v_add_f32_e32 v122, 1.0, v122
	v_rcp_f32_e32 v122, v122
	s_nop 0
	v_mul_f32_e32 v114, v114, v122
	v_mul_f32_e32 v114, v118, v114
	v_cvt_pk_bf16_f32 v114, v114, s0
	ds_write_b16 v132, v114 offset:32
	v_mul_f32_e32 v114, v123, v166
	v_mul_f32_e32 v122, 0xbfb8aa3b, v114
	v_exp_f32_e32 v122, v122
	v_mul_f32_e32 v118, v127, v166
	v_add_f32_e32 v122, 1.0, v122
	v_rcp_f32_e32 v122, v122
	s_nop 0
	v_mul_f32_e32 v114, v114, v122
	v_mul_f32_e32 v114, v118, v114
	v_cvt_pk_bf16_f32 v114, v114, s0
	ds_write_b16 v132, v114 offset:80
	v_mul_f32_e32 v114, v115, v166
	v_mul_f32_e32 v118, 0xbfb8aa3b, v114
	v_exp_f32_e32 v118, v118
	v_mul_f32_e32 v115, v119, v166
	v_add_f32_e32 v118, 1.0, v118
	v_rcp_f32_e32 v118, v118
	s_nop 0
	v_mul_f32_e32 v114, v114, v118
	v_mul_f32_e32 v114, v115, v114
	v_cvt_pk_bf16_f32 v114, v114, s0
	ds_write_b16 v132, v114 offset:112
	v_mul_f32_e32 v114, v124, v165
	v_mul_f32_e32 v118, 0xbfb8aa3b, v114
	v_exp_f32_e32 v118, v118
	v_mul_f32_e32 v115, v128, v165
	v_add_f32_e32 v118, 1.0, v118
	v_rcp_f32_e32 v118, v118
	s_nop 0
	v_mul_f32_e32 v114, v114, v118
	v_mul_f32_e32 v114, v115, v114
	v_cvt_pk_bf16_f32 v114, v114, s0
	ds_write_b16 v132, v114 offset:160
	v_mul_f32_e32 v114, v116, v165
	v_mul_f32_e32 v116, 0xbfb8aa3b, v114
	v_exp_f32_e32 v116, v116
	v_mul_f32_e32 v115, v120, v165
	v_add_f32_e32 v116, 1.0, v116
	v_rcp_f32_e32 v116, v116
	s_nop 0
	v_mul_f32_e32 v114, v114, v116
	v_mul_f32_e32 v114, v115, v114
	v_cvt_pk_bf16_f32 v114, v114, s0
	ds_write_b16 v132, v114 offset:192
	v_mul_f32_e32 v114, v125, v163
	v_mul_f32_e32 v116, 0xbfb8aa3b, v114
	v_exp_f32_e32 v116, v116
	v_mul_f32_e32 v115, v129, v163
	v_add_f32_e32 v116, 1.0, v116
	v_rcp_f32_e32 v116, v116
	s_nop 0
	v_mul_f32_e32 v114, v114, v116
	v_mul_f32_e32 v114, v115, v114
	v_cvt_pk_bf16_f32 v114, v114, s0
	ds_write_b16 v132, v114 offset:240
	v_mul_f32_e32 v114, v117, v163
	v_mul_f32_e32 v116, 0xbfb8aa3b, v114
	v_exp_f32_e32 v116, v116
	v_mul_f32_e32 v115, v121, v163
	v_add_f32_e32 v116, 1.0, v116
	v_rcp_f32_e32 v116, v116
	s_nop 0
	v_mul_f32_e32 v114, v114, v116
	v_mul_f32_e32 v114, v115, v114
	v_cvt_pk_bf16_f32 v114, v114, s0
	ds_write_b16 v132, v114 offset:272
	ds_read_b128 v[114:117], v0
	s_waitcnt lgkmcnt(0)
	global_store_dwordx4 v[130:131], v[114:117], off
	v_mul_f32_e32 v106, v106, v164
	s_nop 0
	v_mul_f32_e32 v114, 0xbfb8aa3b, v106
	v_exp_f32_e32 v114, v114
	v_mul_f32_e32 v110, v110, v164
	v_mul_f32_e32 v98, v98, v164
	v_mul_f32_e32 v102, v102, v164
	v_add_f32_e32 v114, 1.0, v114
	v_rcp_f32_e32 v114, v114
	s_nop 0
	v_mul_f32_e32 v106, v106, v114
	v_mul_f32_e32 v106, v110, v106
	v_cvt_pk_bf16_f32 v106, v106, s0
	ds_write_b16 v132, v106
	v_mul_f32_e32 v106, 0xbfb8aa3b, v98
	v_exp_f32_e32 v106, v106
	s_nop 0
	v_add_f32_e32 v106, 1.0, v106
	v_rcp_f32_e32 v106, v106
	s_nop 0
	v_mul_f32_e32 v98, v98, v106
	v_mul_f32_e32 v98, v102, v98
	v_cvt_pk_bf16_f32 v98, v98, s0
	ds_write_b16 v132, v98 offset:32
	v_mul_f32_e32 v98, v107, v162
	v_mul_f32_e32 v106, 0xbfb8aa3b, v98
	v_exp_f32_e32 v106, v106
	v_mul_f32_e32 v102, v111, v162
	v_add_f32_e32 v106, 1.0, v106
	v_rcp_f32_e32 v106, v106
	s_nop 0
	v_mul_f32_e32 v98, v98, v106
	v_mul_f32_e32 v98, v102, v98
	v_cvt_pk_bf16_f32 v98, v98, s0
	ds_write_b16 v132, v98 offset:80
	v_mul_f32_e32 v98, v99, v162
	v_mul_f32_e32 v102, 0xbfb8aa3b, v98
	v_exp_f32_e32 v102, v102
	v_mul_f32_e32 v99, v103, v162
	v_add_f32_e32 v102, 1.0, v102
	v_rcp_f32_e32 v102, v102
	s_nop 0
	v_mul_f32_e32 v98, v98, v102
	v_mul_f32_e32 v98, v99, v98
	v_cvt_pk_bf16_f32 v98, v98, s0
	ds_write_b16 v132, v98 offset:112
	v_mul_f32_e32 v98, v108, v161
	v_mul_f32_e32 v102, 0xbfb8aa3b, v98
	v_exp_f32_e32 v102, v102
	v_mul_f32_e32 v99, v112, v161
	v_add_f32_e32 v102, 1.0, v102
	v_rcp_f32_e32 v102, v102
	s_nop 0
	v_mul_f32_e32 v98, v98, v102
	v_mul_f32_e32 v98, v99, v98
	v_cvt_pk_bf16_f32 v98, v98, s0
	ds_write_b16 v132, v98 offset:160
	v_mul_f32_e32 v98, v100, v161
	v_mul_f32_e32 v100, 0xbfb8aa3b, v98
	v_exp_f32_e32 v100, v100
	v_mul_f32_e32 v99, v104, v161
	v_add_f32_e32 v100, 1.0, v100
	v_rcp_f32_e32 v100, v100
	s_nop 0
	v_mul_f32_e32 v98, v98, v100
	v_mul_f32_e32 v98, v99, v98
	v_cvt_pk_bf16_f32 v98, v98, s0
	ds_write_b16 v132, v98 offset:192
	v_mul_f32_e32 v98, v109, v159
	v_mul_f32_e32 v100, 0xbfb8aa3b, v98
	v_exp_f32_e32 v100, v100
	v_mul_f32_e32 v99, v113, v159
	v_add_f32_e32 v100, 1.0, v100
	v_rcp_f32_e32 v100, v100
	s_nop 0
	v_mul_f32_e32 v98, v98, v100
	v_mul_f32_e32 v98, v99, v98
	v_cvt_pk_bf16_f32 v98, v98, s0
	ds_write_b16 v132, v98 offset:240
	v_mul_f32_e32 v98, v101, v159
	v_mul_f32_e32 v100, 0xbfb8aa3b, v98
	v_exp_f32_e32 v100, v100
	v_mul_f32_e32 v99, v105, v159
	v_add_f32_e32 v100, 1.0, v100
	v_rcp_f32_e32 v100, v100
	s_nop 0
	v_mul_f32_e32 v98, v98, v100
	v_mul_f32_e32 v98, v99, v98
	v_cvt_pk_bf16_f32 v98, v98, s0
	ds_write_b16 v132, v98 offset:272
	ds_read_b128 v[98:101], v0
	s_mov_b32 s0, 0x16000
	v_add_co_u32_e32 v102, vcc, s0, v130
	s_nop 1
	v_addc_co_u32_e32 v103, vcc, 0, v131, vcc
	s_waitcnt lgkmcnt(0)
; DI bf16_t to_bf16(float x) { return (bf16_t)(pack_bf16(x, 0.f) & 0xffffu); }
;   DI void run8(f32x4 (&acc)[8][4], int rb, int cb, int fr, int fq) const {
;     ...
;     for (int m = 0; m < 8; ++m) {
; #pragma unroll
;       for (int j = 0; j < 4; ++j)
; #pragma unroll
;         for (int pi = 0; pi < 2; ++pi) {
;           const float g = acc[m][2 * pi][j] * rsv[m][j], u = acc[m][2 * pi + 1][j] * rsv[m][j];
;           const float a = g * __builtin_amdgcn_rcpf(1.f + __expf(-g)) * u;
;           scr[(fq * 4 + j) * 40 + pi * 16 + fr] = to_bf16(a);
;         }
;       __builtin_amdgcn_sched_barrier(0);
;       const u32x4 o = *(const u32x4*)(scr + srow * 40 + sch * 8);
;       *(u32x4*)(ap + (size_t)(m * 16) * LDA) = o;
;       __builtin_amdgcn_sched_barrier(0);
	global_store_dwordx4 v[102:103], v[98:101], off offset:2048
	v_mul_f32_e32 v90, v90, v160
	s_nop 0
	v_mul_f32_e32 v98, 0xbfb8aa3b, v90
	v_exp_f32_e32 v98, v98
	v_mul_f32_e32 v94, v94, v160
	v_mul_f32_e32 v82, v82, v160
	v_mul_f32_e32 v86, v86, v160
	v_add_f32_e32 v98, 1.0, v98
	v_rcp_f32_e32 v98, v98
	s_nop 0
	v_mul_f32_e32 v90, v90, v98
	v_mul_f32_e32 v90, v94, v90
	v_cvt_pk_bf16_f32 v90, v90, s0
	ds_write_b16 v132, v90
	v_mul_f32_e32 v90, 0xbfb8aa3b, v82
	v_exp_f32_e32 v90, v90
	s_nop 0
	v_add_f32_e32 v90, 1.0, v90
	v_rcp_f32_e32 v90, v90
	s_nop 0
	v_mul_f32_e32 v82, v82, v90
	v_mul_f32_e32 v82, v86, v82
	v_cvt_pk_bf16_f32 v82, v82, s0
	ds_write_b16 v132, v82 offset:32
	v_mul_f32_e32 v82, v91, v158
	v_mul_f32_e32 v90, 0xbfb8aa3b, v82
	v_exp_f32_e32 v90, v90
	v_mul_f32_e32 v86, v95, v158
	v_add_f32_e32 v90, 1.0, v90
	v_rcp_f32_e32 v90, v90
	s_nop 0
	v_mul_f32_e32 v82, v82, v90
	v_mul_f32_e32 v82, v86, v82
	v_cvt_pk_bf16_f32 v82, v82, s0
	ds_write_b16 v132, v82 offset:80
	v_mul_f32_e32 v82, v83, v158
	v_mul_f32_e32 v86, 0xbfb8aa3b, v82
	v_exp_f32_e32 v86, v86
	v_mul_f32_e32 v83, v87, v158
	v_add_f32_e32 v86, 1.0, v86
	v_rcp_f32_e32 v86, v86
	s_nop 0
	v_mul_f32_e32 v82, v82, v86
	v_mul_f32_e32 v82, v83, v82
	v_cvt_pk_bf16_f32 v82, v82, s0
	ds_write_b16 v132, v82 offset:112
	v_mul_f32_e32 v82, v92, v157
	v_mul_f32_e32 v86, 0xbfb8aa3b, v82
	v_exp_f32_e32 v86, v86
	v_mul_f32_e32 v83, v96, v157
	v_add_f32_e32 v86, 1.0, v86
	v_rcp_f32_e32 v86, v86
	s_nop 0
	v_mul_f32_e32 v82, v82, v86
	v_mul_f32_e32 v82, v83, v82
	v_cvt_pk_bf16_f32 v82, v82, s0
	ds_write_b16 v132, v82 offset:160
	v_mul_f32_e32 v82, v84, v157
	v_mul_f32_e32 v84, 0xbfb8aa3b, v82
	v_exp_f32_e32 v84, v84
	v_mul_f32_e32 v83, v88, v157
	v_add_f32_e32 v84, 1.0, v84
	v_rcp_f32_e32 v84, v84
	s_nop 0
	v_mul_f32_e32 v82, v82, v84
	v_mul_f32_e32 v82, v83, v82
	v_cvt_pk_bf16_f32 v82, v82, s0
	ds_write_b16 v132, v82 offset:192
	v_mul_f32_e32 v82, v93, v155
	v_mul_f32_e32 v84, 0xbfb8aa3b, v82
	v_exp_f32_e32 v84, v84
	v_mul_f32_e32 v83, v97, v155
	v_add_f32_e32 v84, 1.0, v84
	v_rcp_f32_e32 v84, v84
	s_nop 0
	v_mul_f32_e32 v82, v82, v84
	v_mul_f32_e32 v82, v83, v82
	v_cvt_pk_bf16_f32 v82, v82, s0
	ds_write_b16 v132, v82 offset:240
	v_mul_f32_e32 v82, v85, v155
	v_mul_f32_e32 v84, 0xbfb8aa3b, v82
	v_exp_f32_e32 v84, v84
	v_mul_f32_e32 v83, v89, v155
	v_add_f32_e32 v84, 1.0, v84
	v_rcp_f32_e32 v84, v84
	s_nop 0
	v_mul_f32_e32 v82, v82, v84
	v_mul_f32_e32 v82, v83, v82
	v_cvt_pk_bf16_f32 v82, v82, s0
	ds_write_b16 v132, v82 offset:272
	ds_read_b128 v[82:85], v0
	s_mov_b32 s0, 0x2d000
	v_add_co_u32_e32 v86, vcc, s0, v130
	s_nop 1
	v_addc_co_u32_e32 v87, vcc, 0, v131, vcc
	s_waitcnt lgkmcnt(0)
	global_store_dwordx4 v[86:87], v[82:85], off
	v_mul_f32_e32 v74, v74, v156
	s_nop 0
	v_mul_f32_e32 v82, 0xbfb8aa3b, v74
	v_exp_f32_e32 v82, v82
	v_mul_f32_e32 v78, v78, v156
	v_mul_f32_e32 v66, v66, v156
	v_mul_f32_e32 v70, v70, v156
	v_add_f32_e32 v82, 1.0, v82
	v_rcp_f32_e32 v82, v82
	s_nop 0
	v_mul_f32_e32 v74, v74, v82
	v_mul_f32_e32 v74, v78, v74
	v_cvt_pk_bf16_f32 v74, v74, s0
	ds_write_b16 v132, v74
	v_mul_f32_e32 v74, 0xbfb8aa3b, v66
	v_exp_f32_e32 v74, v74
	s_nop 0
	v_add_f32_e32 v74, 1.0, v74
	v_rcp_f32_e32 v74, v74
	s_nop 0
	v_mul_f32_e32 v66, v66, v74
	v_mul_f32_e32 v66, v70, v66
	v_cvt_pk_bf16_f32 v66, v66, s0
	ds_write_b16 v132, v66 offset:32
	v_mul_f32_e32 v66, v75, v154
	v_mul_f32_e32 v74, 0xbfb8aa3b, v66
	v_exp_f32_e32 v74, v74
	v_mul_f32_e32 v70, v79, v154
	v_add_f32_e32 v74, 1.0, v74
	v_rcp_f32_e32 v74, v74
	s_nop 0
	v_mul_f32_e32 v66, v66, v74
	v_mul_f32_e32 v66, v70, v66
	v_cvt_pk_bf16_f32 v66, v66, s0
	ds_write_b16 v132, v66 offset:80
	v_mul_f32_e32 v66, v67, v154
	v_mul_f32_e32 v70, 0xbfb8aa3b, v66
	v_exp_f32_e32 v70, v70
	v_mul_f32_e32 v67, v71, v154
	v_add_f32_e32 v70, 1.0, v70
	v_rcp_f32_e32 v70, v70
	s_nop 0
	v_mul_f32_e32 v66, v66, v70
	v_mul_f32_e32 v66, v67, v66
	v_cvt_pk_bf16_f32 v66, v66, s0
	ds_write_b16 v132, v66 offset:112
	v_mul_f32_e32 v66, v76, v153
	v_mul_f32_e32 v70, 0xbfb8aa3b, v66
	v_exp_f32_e32 v70, v70
	v_mul_f32_e32 v67, v80, v153
	v_add_f32_e32 v70, 1.0, v70
	v_rcp_f32_e32 v70, v70
	s_nop 0
	v_mul_f32_e32 v66, v66, v70
	v_mul_f32_e32 v66, v67, v66
	v_cvt_pk_bf16_f32 v66, v66, s0
	ds_write_b16 v132, v66 offset:160
	v_mul_f32_e32 v66, v68, v153
	v_mul_f32_e32 v68, 0xbfb8aa3b, v66
	v_exp_f32_e32 v68, v68
	v_mul_f32_e32 v67, v72, v153
	v_add_f32_e32 v68, 1.0, v68
	v_rcp_f32_e32 v68, v68
	s_nop 0
	v_mul_f32_e32 v66, v66, v68
	v_mul_f32_e32 v66, v67, v66
	v_cvt_pk_bf16_f32 v66, v66, s0
	ds_write_b16 v132, v66 offset:192
	v_mul_f32_e32 v66, v77, v150
	v_mul_f32_e32 v68, 0xbfb8aa3b, v66
	v_exp_f32_e32 v68, v68
	v_mul_f32_e32 v67, v81, v150
	v_add_f32_e32 v68, 1.0, v68
	v_rcp_f32_e32 v68, v68
	s_nop 0
	v_mul_f32_e32 v66, v66, v68
	v_mul_f32_e32 v66, v67, v66
	v_cvt_pk_bf16_f32 v66, v66, s0
	ds_write_b16 v132, v66 offset:240
	v_mul_f32_e32 v66, v69, v150
	v_mul_f32_e32 v68, 0xbfb8aa3b, v66
	v_exp_f32_e32 v68, v68
	v_mul_f32_e32 v67, v73, v150
	v_add_f32_e32 v68, 1.0, v68
	v_rcp_f32_e32 v68, v68
	s_nop 0
	v_mul_f32_e32 v66, v66, v68
	v_mul_f32_e32 v66, v67, v66
	v_cvt_pk_bf16_f32 v66, v66, s0
	ds_write_b16 v132, v66 offset:272
	ds_read_b128 v[66:69], v0
	s_mov_b32 s0, 0x43000
	v_add_co_u32_e32 v70, vcc, s0, v130
	s_nop 1
	v_addc_co_u32_e32 v71, vcc, 0, v131, vcc
	s_waitcnt lgkmcnt(0)
; DI bf16_t to_bf16(float x) { return (bf16_t)(pack_bf16(x, 0.f) & 0xffffu); }
;   DI void run8(f32x4 (&acc)[8][4], int rb, int cb, int fr, int fq) const {
;     ...
;     for (int m = 0; m < 8; ++m) {
; #pragma unroll
;       for (int j = 0; j < 4; ++j)
; #pragma unroll
;         for (int pi = 0; pi < 2; ++pi) {
;           const float g = acc[m][2 * pi][j] * rsv[m][j], u = acc[m][2 * pi + 1][j] * rsv[m][j];
;           const float a = g * __builtin_amdgcn_rcpf(1.f + __expf(-g)) * u;
;           scr[(fq * 4 + j) * 40 + pi * 16 + fr] = to_bf16(a);
;         }
;       __builtin_amdgcn_sched_barrier(0);
;       const u32x4 o = *(const u32x4*)(scr + srow * 40 + sch * 8);
;       *(u32x4*)(ap + (size_t)(m * 16) * LDA) = o;
;       __builtin_amdgcn_sched_barrier(0);
	global_store_dwordx4 v[70:71], v[66:69], off offset:2048
	v_mul_f32_e32 v58, v58, v151
	s_nop 0
	v_mul_f32_e32 v66, 0xbfb8aa3b, v58
	v_exp_f32_e32 v66, v66
	v_mul_f32_e32 v62, v62, v151
	v_mul_f32_e32 v50, v50, v151
	v_mul_f32_e32 v54, v54, v151
	v_add_f32_e32 v66, 1.0, v66
	v_rcp_f32_e32 v66, v66
	s_nop 0
	v_mul_f32_e32 v58, v58, v66
	v_mul_f32_e32 v58, v62, v58
	v_cvt_pk_bf16_f32 v58, v58, s0
	ds_write_b16 v132, v58
	v_mul_f32_e32 v58, 0xbfb8aa3b, v50
	v_exp_f32_e32 v58, v58
	s_nop 0
	v_add_f32_e32 v58, 1.0, v58
	v_rcp_f32_e32 v58, v58
	s_nop 0
	v_mul_f32_e32 v50, v50, v58
	v_mul_f32_e32 v50, v54, v50
	v_cvt_pk_bf16_f32 v50, v50, s0
	ds_write_b16 v132, v50 offset:32
	v_mul_f32_e32 v50, v59, v148
	v_mul_f32_e32 v58, 0xbfb8aa3b, v50
	v_exp_f32_e32 v58, v58
	v_mul_f32_e32 v54, v63, v148
	v_add_f32_e32 v58, 1.0, v58
	v_rcp_f32_e32 v58, v58
	s_nop 0
	v_mul_f32_e32 v50, v50, v58
	v_mul_f32_e32 v50, v54, v50
	v_cvt_pk_bf16_f32 v50, v50, s0
	ds_write_b16 v132, v50 offset:80
	v_mul_f32_e32 v50, v51, v148
	v_mul_f32_e32 v54, 0xbfb8aa3b, v50
	v_exp_f32_e32 v54, v54
	v_mul_f32_e32 v51, v55, v148
	v_add_f32_e32 v54, 1.0, v54
	v_rcp_f32_e32 v54, v54
	s_nop 0
	v_mul_f32_e32 v50, v50, v54
	v_mul_f32_e32 v50, v51, v50
	v_cvt_pk_bf16_f32 v50, v50, s0
	ds_write_b16 v132, v50 offset:112
	v_mul_f32_e32 v50, v60, v146
	v_mul_f32_e32 v54, 0xbfb8aa3b, v50
	v_exp_f32_e32 v54, v54
	v_mul_f32_e32 v51, v64, v146
	v_add_f32_e32 v54, 1.0, v54
	v_rcp_f32_e32 v54, v54
	s_nop 0
	v_mul_f32_e32 v50, v50, v54
	v_mul_f32_e32 v50, v51, v50
	v_cvt_pk_bf16_f32 v50, v50, s0
	ds_write_b16 v132, v50 offset:160
	v_mul_f32_e32 v50, v52, v146
	v_mul_f32_e32 v52, 0xbfb8aa3b, v50
	v_exp_f32_e32 v52, v52
	v_mul_f32_e32 v51, v56, v146
	v_add_f32_e32 v52, 1.0, v52
	v_rcp_f32_e32 v52, v52
	s_nop 0
	v_mul_f32_e32 v50, v50, v52
	v_mul_f32_e32 v50, v51, v50
	v_cvt_pk_bf16_f32 v50, v50, s0
	ds_write_b16 v132, v50 offset:192
	v_mul_f32_e32 v50, v61, v143
	v_mul_f32_e32 v52, 0xbfb8aa3b, v50
	v_exp_f32_e32 v52, v52
	v_mul_f32_e32 v51, v65, v143
	v_add_f32_e32 v52, 1.0, v52
	v_rcp_f32_e32 v52, v52
	s_nop 0
	v_mul_f32_e32 v50, v50, v52
	v_mul_f32_e32 v50, v51, v50
	v_cvt_pk_bf16_f32 v50, v50, s0
	ds_write_b16 v132, v50 offset:240
	v_mul_f32_e32 v50, v53, v143
	v_mul_f32_e32 v52, 0xbfb8aa3b, v50
	v_exp_f32_e32 v52, v52
	v_mul_f32_e32 v51, v57, v143
	v_add_f32_e32 v52, 1.0, v52
	v_rcp_f32_e32 v52, v52
	s_nop 0
	v_mul_f32_e32 v50, v50, v52
	v_mul_f32_e32 v50, v51, v50
	v_cvt_pk_bf16_f32 v50, v50, s0
	ds_write_b16 v132, v50 offset:272
	ds_read_b128 v[50:53], v0
	s_mov_b32 s0, 0x5a000
	v_add_co_u32_e32 v54, vcc, s0, v130
	s_nop 1
	v_addc_co_u32_e32 v55, vcc, 0, v131, vcc
	s_waitcnt lgkmcnt(0)
	global_store_dwordx4 v[54:55], v[50:53], off
	v_mul_f32_e32 v42, v42, v145
	s_nop 0
	v_mul_f32_e32 v50, 0xbfb8aa3b, v42
	v_exp_f32_e32 v50, v50
	v_mul_f32_e32 v46, v46, v145
	v_mul_f32_e32 v34, v34, v145
	v_mul_f32_e32 v38, v38, v145
	v_add_f32_e32 v50, 1.0, v50
	v_rcp_f32_e32 v50, v50
	s_nop 0
	v_mul_f32_e32 v42, v42, v50
	v_mul_f32_e32 v42, v46, v42
	v_cvt_pk_bf16_f32 v42, v42, s0
	ds_write_b16 v132, v42
	v_mul_f32_e32 v42, 0xbfb8aa3b, v34
	v_exp_f32_e32 v42, v42
	s_nop 0
	v_add_f32_e32 v42, 1.0, v42
	v_rcp_f32_e32 v42, v42
	s_nop 0
	v_mul_f32_e32 v34, v34, v42
	v_mul_f32_e32 v34, v38, v34
	v_cvt_pk_bf16_f32 v34, v34, s0
	ds_write_b16 v132, v34 offset:32
	v_mul_f32_e32 v34, v43, v142
	v_mul_f32_e32 v42, 0xbfb8aa3b, v34
	v_exp_f32_e32 v42, v42
	v_mul_f32_e32 v38, v47, v142
	v_add_f32_e32 v42, 1.0, v42
	v_rcp_f32_e32 v42, v42
	s_nop 0
	v_mul_f32_e32 v34, v34, v42
	v_mul_f32_e32 v34, v38, v34
	v_cvt_pk_bf16_f32 v34, v34, s0
	ds_write_b16 v132, v34 offset:80
	v_mul_f32_e32 v34, v35, v142
	v_mul_f32_e32 v38, 0xbfb8aa3b, v34
	v_exp_f32_e32 v38, v38
	v_mul_f32_e32 v35, v39, v142
	v_add_f32_e32 v38, 1.0, v38
	v_rcp_f32_e32 v38, v38
	s_nop 0
	v_mul_f32_e32 v34, v34, v38
	v_mul_f32_e32 v34, v35, v34
	v_cvt_pk_bf16_f32 v34, v34, s0
	ds_write_b16 v132, v34 offset:112
	v_mul_f32_e32 v34, v44, v140
	v_mul_f32_e32 v38, 0xbfb8aa3b, v34
	v_exp_f32_e32 v38, v38
	v_mul_f32_e32 v35, v48, v140
	v_add_f32_e32 v38, 1.0, v38
	v_rcp_f32_e32 v38, v38
	s_nop 0
	v_mul_f32_e32 v34, v34, v38
	v_mul_f32_e32 v34, v35, v34
	v_cvt_pk_bf16_f32 v34, v34, s0
	ds_write_b16 v132, v34 offset:160
	v_mul_f32_e32 v34, v36, v140
	v_mul_f32_e32 v36, 0xbfb8aa3b, v34
	v_exp_f32_e32 v36, v36
	v_mul_f32_e32 v35, v40, v140
	v_add_f32_e32 v36, 1.0, v36
	v_rcp_f32_e32 v36, v36
	s_nop 0
	v_mul_f32_e32 v34, v34, v36
	v_mul_f32_e32 v34, v35, v34
	v_cvt_pk_bf16_f32 v34, v34, s0
	ds_write_b16 v132, v34 offset:192
	v_mul_f32_e32 v34, v45, v138
	v_mul_f32_e32 v36, 0xbfb8aa3b, v34
	v_exp_f32_e32 v36, v36
	v_mul_f32_e32 v35, v49, v138
	v_add_f32_e32 v36, 1.0, v36
	v_rcp_f32_e32 v36, v36
	s_nop 0
	v_mul_f32_e32 v34, v34, v36
	v_mul_f32_e32 v34, v35, v34
	v_cvt_pk_bf16_f32 v34, v34, s0
	ds_write_b16 v132, v34 offset:240
	v_mul_f32_e32 v34, v37, v138
	v_mul_f32_e32 v36, 0xbfb8aa3b, v34
	v_exp_f32_e32 v36, v36
	v_mul_f32_e32 v35, v41, v138
	v_add_f32_e32 v36, 1.0, v36
	v_rcp_f32_e32 v36, v36
	s_nop 0
	v_mul_f32_e32 v34, v34, v36
	v_mul_f32_e32 v34, v35, v34
	v_cvt_pk_bf16_f32 v34, v34, s0
	ds_write_b16 v132, v34 offset:272
	ds_read_b128 v[34:37], v0
	v_add_co_u32_e32 v38, vcc, s68, v130
	s_nop 1
	v_addc_co_u32_e32 v39, vcc, 0, v131, vcc
	s_waitcnt lgkmcnt(0)
; DI bf16_t to_bf16(float x) { return (bf16_t)(pack_bf16(x, 0.f) & 0xffffu); }
; template <class Epi>
; DI void gemm8_tile(const bf16_t* __restrict__ Ab, int lda, const bf16_t* __restrict__ Bb, int ldb, int K, int brow, int bcol, const Epi epi,
;                    bool staged, bool has_next, const bf16_t* __restrict__ Abn, const bf16_t* __restrict__ Bbn) {
;     ...
;   if (Epi::LDS_SCRATCH) __syncthreads();
;   DI void run8(f32x4 (&acc)[8][4], int rb, int cb, int fr, int fq) const {
;     ...
;     for (int m = 0; m < 8; ++m) {
; #pragma unroll
;       for (int j = 0; j < 4; ++j)
; #pragma unroll
;         for (int pi = 0; pi < 2; ++pi) {
;           const float g = acc[m][2 * pi][j] * rsv[m][j], u = acc[m][2 * pi + 1][j] * rsv[m][j];
;           const float a = g * __builtin_amdgcn_rcpf(1.f + __expf(-g)) * u;
;           scr[(fq * 4 + j) * 40 + pi * 16 + fr] = to_bf16(a);
;         }
;       __builtin_amdgcn_sched_barrier(0);
;       const u32x4 o = *(const u32x4*)(scr + srow * 40 + sch * 8);
;       *(u32x4*)(ap + (size_t)(m * 16) * LDA) = o;
;       __builtin_amdgcn_sched_barrier(0);
	global_store_dwordx4 v[38:39], v[34:37], off offset:2048
	v_mul_f32_e32 v26, v26, v147
	s_nop 0
	v_mul_f32_e32 v34, 0xbfb8aa3b, v26
	v_exp_f32_e32 v34, v34
	v_mul_f32_e32 v30, v30, v147
	v_mul_f32_e32 v18, v18, v147
	v_mul_f32_e32 v22, v22, v147
	v_add_f32_e32 v34, 1.0, v34
	v_rcp_f32_e32 v34, v34
	s_nop 0
	v_mul_f32_e32 v26, v26, v34
	v_mul_f32_e32 v26, v30, v26
	v_cvt_pk_bf16_f32 v26, v26, s0
	ds_write_b16 v132, v26
	v_mul_f32_e32 v26, 0xbfb8aa3b, v18
	v_exp_f32_e32 v26, v26
	s_nop 0
	v_add_f32_e32 v26, 1.0, v26
	v_rcp_f32_e32 v26, v26
	s_nop 0
	v_mul_f32_e32 v18, v18, v26
	v_mul_f32_e32 v18, v22, v18
	v_cvt_pk_bf16_f32 v18, v18, s0
	ds_write_b16 v132, v18 offset:32
	v_mul_f32_e32 v18, v27, v144
	v_mul_f32_e32 v26, 0xbfb8aa3b, v18
	v_exp_f32_e32 v26, v26
	v_mul_f32_e32 v22, v31, v144
	v_add_f32_e32 v26, 1.0, v26
	v_rcp_f32_e32 v26, v26
	s_nop 0
	v_mul_f32_e32 v18, v18, v26
	v_mul_f32_e32 v18, v22, v18
	v_cvt_pk_bf16_f32 v18, v18, s0
	ds_write_b16 v132, v18 offset:80
	v_mul_f32_e32 v18, v19, v144
	v_mul_f32_e32 v22, 0xbfb8aa3b, v18
	v_exp_f32_e32 v22, v22
	v_mul_f32_e32 v19, v23, v144
	v_add_f32_e32 v22, 1.0, v22
	v_rcp_f32_e32 v22, v22
	s_nop 0
	v_mul_f32_e32 v18, v18, v22
	v_mul_f32_e32 v18, v19, v18
	v_cvt_pk_bf16_f32 v18, v18, s0
	ds_write_b16 v132, v18 offset:112
	v_mul_f32_e32 v18, v28, v141
	v_mul_f32_e32 v22, 0xbfb8aa3b, v18
	v_exp_f32_e32 v22, v22
	v_mul_f32_e32 v19, v32, v141
	v_add_f32_e32 v22, 1.0, v22
	v_rcp_f32_e32 v22, v22
	s_nop 0
	v_mul_f32_e32 v18, v18, v22
	v_mul_f32_e32 v18, v19, v18
	v_cvt_pk_bf16_f32 v18, v18, s0
	ds_write_b16 v132, v18 offset:160
	v_mul_f32_e32 v18, v20, v141
	v_mul_f32_e32 v20, 0xbfb8aa3b, v18
	v_exp_f32_e32 v20, v20
	v_mul_f32_e32 v19, v24, v141
	v_add_f32_e32 v20, 1.0, v20
	v_rcp_f32_e32 v20, v20
	s_nop 0
	v_mul_f32_e32 v18, v18, v20
	v_mul_f32_e32 v18, v19, v18
	v_cvt_pk_bf16_f32 v18, v18, s0
	ds_write_b16 v132, v18 offset:192
	v_mul_f32_e32 v18, v29, v139
	v_mul_f32_e32 v20, 0xbfb8aa3b, v18
	v_exp_f32_e32 v20, v20
	v_mul_f32_e32 v19, v33, v139
	v_add_f32_e32 v20, 1.0, v20
	v_rcp_f32_e32 v20, v20
	s_nop 0
	v_mul_f32_e32 v18, v18, v20
	v_mul_f32_e32 v18, v19, v18
	v_cvt_pk_bf16_f32 v18, v18, s0
	ds_write_b16 v132, v18 offset:240
	v_mul_f32_e32 v18, v21, v139
	v_mul_f32_e32 v20, 0xbfb8aa3b, v18
	v_exp_f32_e32 v20, v20
	v_mul_f32_e32 v19, v25, v139
	v_add_f32_e32 v20, 1.0, v20
	v_rcp_f32_e32 v20, v20
	s_nop 0
	v_mul_f32_e32 v18, v18, v20
	v_mul_f32_e32 v18, v19, v18
	v_cvt_pk_bf16_f32 v18, v18, s0
	ds_write_b16 v132, v18 offset:272
	ds_read_b128 v[18:21], v0
	s_mov_b32 s0, 0x87000
	v_add_co_u32_e32 v22, vcc, s0, v130
	s_nop 1
	v_addc_co_u32_e32 v23, vcc, 0, v131, vcc
	s_waitcnt lgkmcnt(0)
	global_store_dwordx4 v[22:23], v[18:21], off
	v_mul_f32_e32 v10, v10, v152
	s_nop 0
	v_mul_f32_e32 v18, 0xbfb8aa3b, v10
	v_exp_f32_e32 v18, v18
	v_mul_f32_e32 v14, v14, v152
	v_mul_f32_e32 v2, v2, v152
	v_mul_f32_e32 v6, v6, v152
	v_add_f32_e32 v18, 1.0, v18
	v_rcp_f32_e32 v18, v18
	s_nop 0
	v_mul_f32_e32 v10, v10, v18
	v_mul_f32_e32 v10, v14, v10
	v_cvt_pk_bf16_f32 v10, v10, s0
	ds_write_b16 v132, v10
	v_mul_f32_e32 v10, 0xbfb8aa3b, v2
	v_exp_f32_e32 v10, v10
	s_nop 0
	v_add_f32_e32 v10, 1.0, v10
	v_rcp_f32_e32 v10, v10
	s_nop 0
	v_mul_f32_e32 v2, v2, v10
	v_mul_f32_e32 v2, v6, v2
	v_cvt_pk_bf16_f32 v2, v2, s0
	ds_write_b16 v132, v2 offset:32
	v_mul_f32_e32 v2, v11, v149
	v_mul_f32_e32 v10, 0xbfb8aa3b, v2
	v_exp_f32_e32 v10, v10
	v_mul_f32_e32 v6, v15, v149
	v_add_f32_e32 v10, 1.0, v10
	v_rcp_f32_e32 v10, v10
	s_nop 0
	v_mul_f32_e32 v2, v2, v10
	v_mul_f32_e32 v2, v6, v2
	v_cvt_pk_bf16_f32 v2, v2, s0
	ds_write_b16 v132, v2 offset:80
	v_mul_f32_e32 v2, v3, v149
	v_mul_f32_e32 v6, 0xbfb8aa3b, v2
	v_exp_f32_e32 v6, v6
	v_mul_f32_e32 v3, v7, v149
	v_add_f32_e32 v6, 1.0, v6
	v_rcp_f32_e32 v6, v6
	s_nop 0
	v_mul_f32_e32 v2, v2, v6
	v_mul_f32_e32 v2, v3, v2
	v_cvt_pk_bf16_f32 v2, v2, s0
	ds_write_b16 v132, v2 offset:112
	v_mul_f32_e32 v2, v12, v136
	v_mul_f32_e32 v6, 0xbfb8aa3b, v2
	v_exp_f32_e32 v6, v6
	v_mul_f32_e32 v3, v16, v136
	v_add_f32_e32 v6, 1.0, v6
	v_rcp_f32_e32 v6, v6
	s_nop 0
	v_mul_f32_e32 v2, v2, v6
	v_mul_f32_e32 v2, v3, v2
	v_cvt_pk_bf16_f32 v2, v2, s0
	ds_write_b16 v132, v2 offset:160
	v_mul_f32_e32 v2, v4, v136
	v_mul_f32_e32 v4, 0xbfb8aa3b, v2
	v_exp_f32_e32 v4, v4
	v_mul_f32_e32 v3, v8, v136
	v_add_f32_e32 v4, 1.0, v4
	v_rcp_f32_e32 v4, v4
	s_nop 0
	v_mul_f32_e32 v2, v2, v4
	v_mul_f32_e32 v2, v3, v2
	v_cvt_pk_bf16_f32 v2, v2, s0
	ds_write_b16 v132, v2 offset:192
	v_mul_f32_e32 v2, v13, v133
	v_mul_f32_e32 v4, 0xbfb8aa3b, v2
	v_exp_f32_e32 v4, v4
	v_mul_f32_e32 v3, v17, v133
	v_add_f32_e32 v4, 1.0, v4
	v_rcp_f32_e32 v4, v4
	s_nop 0
	v_mul_f32_e32 v2, v2, v4
	v_mul_f32_e32 v2, v3, v2
	v_cvt_pk_bf16_f32 v2, v2, s0
	ds_write_b16 v132, v2 offset:240
	v_mul_f32_e32 v2, v5, v133
	v_mul_f32_e32 v4, 0xbfb8aa3b, v2
	v_exp_f32_e32 v4, v4
	v_mul_f32_e32 v3, v9, v133
	v_add_f32_e32 v4, 1.0, v4
	v_rcp_f32_e32 v4, v4
	s_nop 0
	v_mul_f32_e32 v2, v2, v4
	v_mul_f32_e32 v2, v3, v2
	v_cvt_pk_bf16_f32 v2, v2, s0
	ds_write_b16 v132, v2 offset:272
	ds_read_b128 v[2:5], v0
	v_add_co_u32_e32 v6, vcc, 0x9d000, v130
	s_nop 1
	v_addc_co_u32_e32 v7, vcc, 0, v131, vcc
	s_waitcnt lgkmcnt(0)
	global_store_dwordx4 v[6:7], v[2:5], off offset:2048
	s_andn2_b64 vcc, exec, s[6:7]
	s_mov_b64 s[56:57], -1
	s_barrier
	s_cbranch_vccz .LBB0_467

; #define MFMA16(a, b, c) __builtin_amdgcn_mfma_f32_16x16x32_bf16((a), (b), (c), 0, 0, 0)
; template <class Epi>
; DI void gemm8_tile(const bf16_t* __restrict__ Ab, int lda, const bf16_t* __restrict__ Bb, int ldb, int K, int brow, int bcol, const Epi epi,
;                    bool staged, bool has_next, const bf16_t* __restrict__ Abn, const bf16_t* __restrict__ Bbn) {
;     ...
;         for (int n = 0; n < 4; ++n) acc[m][n] = MFMA16(At[m], Bf[n], acc[m][n]);
;       __builtin_amdgcn_sched_barrier(0);
;     }
;     asm volatile("s_waitcnt vmcnt(0)" ::: "memory");
;     __syncthreads();
;   }
;     ...
;   epi.run8(acc, brow + wr * 128, bcol + wc * 64, fr, fq);
;   if (Epi::LDS_SCRATCH) __syncthreads();
;   DI void run8(f32x4 (&acc)[8][4], int rb, int cb, int fr, int fq) const {
;     ...
;     for (int m = 0; m < 8; ++m)
; #pragma unroll
;       for (int j = 0; j < 4; ++j) rsv[m][j] = rsqrtf(ssq[rb + m * 16 + fq * 4 + j] * (1.f / D) + EPS);
.LBB0_1667:
	s_waitcnt lgkmcnt(0)
	v_lshrrev_b32_e32 v250, 4, v228
	v_add_u32_e32 v248, s3, v230
	v_lshl_or_b32 v248, v250, 2, v248
	v_ashrrev_i32_e32 v249, 31, v248
	v_lshl_add_u64 v[248:249], v[248:249], 2, s[60:61]
	global_load_dwordx4 v[212:215], v[248:249], off
	global_load_dwordx4 v[224:227], v[248:249], off offset:64
	global_load_dwordx4 v[232:235], v[248:249], off offset:128
	global_load_dwordx4 v[236:239], v[248:249], off offset:192
	global_load_dwordx4 v[240:243], v[248:249], off offset:256
	global_load_dwordx4 v[244:247], v[248:249], off offset:320
	v_mfma_f32_16x16x32_bf16 v[122:125], v[58:61], v[2:5], v[126:129]
	v_mfma_f32_16x16x32_bf16 v[126:129], v[58:61], v[138:141], v[146:149]
	v_mfma_f32_16x16x32_bf16 v[114:117], v[58:61], v[142:145], v[118:121]
	v_mfma_f32_16x16x32_bf16 v[118:121], v[58:61], v[202:205], v[150:153]
	v_mfma_f32_16x16x32_bf16 v[106:109], v[50:53], v[2:5], v[110:113]
	v_mfma_f32_16x16x32_bf16 v[110:113], v[50:53], v[138:141], v[154:157]
	v_mfma_f32_16x16x32_bf16 v[98:101], v[50:53], v[142:145], v[102:105]
	v_mfma_f32_16x16x32_bf16 v[102:105], v[50:53], v[202:205], v[158:161]
	v_mfma_f32_16x16x32_bf16 v[90:93], v[42:45], v[2:5], v[94:97]
	v_mfma_f32_16x16x32_bf16 v[94:97], v[42:45], v[138:141], v[162:165]
	v_mfma_f32_16x16x32_bf16 v[82:85], v[42:45], v[142:145], v[86:89]
	v_mfma_f32_16x16x32_bf16 v[86:89], v[42:45], v[202:205], v[166:169]
	v_mfma_f32_16x16x32_bf16 v[74:77], v[34:37], v[2:5], v[78:81]
	v_mfma_f32_16x16x32_bf16 v[78:81], v[34:37], v[138:141], v[170:173]
	v_mfma_f32_16x16x32_bf16 v[66:69], v[34:37], v[142:145], v[70:73]
	v_mfma_f32_16x16x32_bf16 v[70:73], v[34:37], v[202:205], v[174:177]
	global_load_dwordx4 v[170:173], v[248:249], off offset:384
	global_load_dwordx4 v[174:177], v[248:249], off offset:448
	v_mfma_f32_16x16x32_bf16 v[58:61], v[26:29], v[2:5], v[62:65]
	v_mfma_f32_16x16x32_bf16 v[62:65], v[26:29], v[138:141], v[178:181]
	v_mfma_f32_16x16x32_bf16 v[50:53], v[26:29], v[142:145], v[54:57]
	v_mfma_f32_16x16x32_bf16 v[54:57], v[26:29], v[202:205], v[182:185]
	v_mfma_f32_16x16x32_bf16 v[42:45], v[18:21], v[2:5], v[46:49]
	v_mfma_f32_16x16x32_bf16 v[46:49], v[18:21], v[138:141], v[186:189]
	v_mfma_f32_16x16x32_bf16 v[34:37], v[18:21], v[142:145], v[38:41]
	v_mfma_f32_16x16x32_bf16 v[38:41], v[18:21], v[202:205], v[190:193]
	v_mfma_f32_16x16x32_bf16 v[26:29], v[10:13], v[2:5], v[30:33]
	v_mfma_f32_16x16x32_bf16 v[30:33], v[10:13], v[138:141], v[194:197]
	v_mfma_f32_16x16x32_bf16 v[18:21], v[10:13], v[142:145], v[22:25]
	v_mfma_f32_16x16x32_bf16 v[22:25], v[10:13], v[202:205], v[198:201]
	v_mfma_f32_16x16x32_bf16 v[10:13], v[206:209], v[2:5], v[14:17]
	v_mfma_f32_16x16x32_bf16 v[14:17], v[206:209], v[138:141], v[130:133]
	v_mfma_f32_16x16x32_bf16 v[2:5], v[206:209], v[142:145], v[6:9]
	v_mfma_f32_16x16x32_bf16 v[6:9], v[206:209], v[202:205], v[134:137]
	v_lshrrev_b32_e32 v168, 4, v228
	v_add_u32_e32 v130, s3, v230
	v_lshl_or_b32 v131, v229, 6, s31
	v_or_b32_e32 v0, v130, v222
	v_lshl_or_b32 v130, v168, 2, v130
	v_ashrrev_i32_e32 v134, 1, v131
	v_ashrrev_i32_e32 v131, 31, v130
	v_lshl_add_u64 v[130:131], v[130:131], 2, s[60:61]
	s_waitcnt vmcnt(8)
	s_waitcnt vmcnt(8)
	s_barrier
	s_mov_b32 s0, 0x358637bd
	v_mov_b64_e32 v[136:137], s[0:1]
	v_ashrrev_i32_e32 v135, 31, v134
	s_waitcnt vmcnt(7)
	v_pk_fma_f32 v[132:133], v[212:213], s[86:87], v[136:137] op_sel_hi:[1,0,0]
	v_rsq_f32_e32 v167, v132
	s_nop 0
	v_mul_f32_e32 v122, v122, v167
	v_mul_f32_e32 v126, v126, v167
	v_mul_f32_e32 v114, v114, v167
	v_rsq_f32_e32 v166, v133
	v_pk_fma_f32 v[132:133], v[214:215], s[86:87], v[136:137] op_sel_hi:[1,0,0]
	v_mul_f32_e32 v118, v118, v167
	v_rsq_f32_e32 v165, v132
	v_rsq_f32_e32 v163, v133
	s_waitcnt vmcnt(6)
	v_pk_fma_f32 v[132:133], v[224:225], s[86:87], v[136:137] op_sel_hi:[1,0,0]
	v_rsq_f32_e32 v164, v132
	v_rsq_f32_e32 v162, v133
	v_pk_fma_f32 v[132:133], v[226:227], s[86:87], v[136:137] op_sel_hi:[1,0,0]
	v_rsq_f32_e32 v161, v132
	v_rsq_f32_e32 v159, v133
	s_waitcnt vmcnt(5)
	v_pk_fma_f32 v[132:133], v[232:233], s[86:87], v[136:137] op_sel_hi:[1,0,0]
	v_rsq_f32_e32 v160, v132
	v_rsq_f32_e32 v158, v133
	v_pk_fma_f32 v[132:133], v[234:235], s[86:87], v[136:137] op_sel_hi:[1,0,0]
	v_rsq_f32_e32 v157, v132
	v_rsq_f32_e32 v155, v133
	s_waitcnt vmcnt(4)
	v_pk_fma_f32 v[132:133], v[236:237], s[86:87], v[136:137] op_sel_hi:[1,0,0]
	v_rsq_f32_e32 v156, v132
	v_rsq_f32_e32 v154, v133
	v_pk_fma_f32 v[132:133], v[238:239], s[86:87], v[136:137] op_sel_hi:[1,0,0]
	v_rsq_f32_e32 v153, v132
	v_rsq_f32_e32 v150, v133
	s_waitcnt vmcnt(3)
	v_pk_fma_f32 v[132:133], v[240:241], s[86:87], v[136:137] op_sel_hi:[1,0,0]
	v_rsq_f32_e32 v151, v132
	v_rsq_f32_e32 v148, v133
	v_pk_fma_f32 v[132:133], v[242:243], s[86:87], v[136:137] op_sel_hi:[1,0,0]
	v_rsq_f32_e32 v146, v132
	v_rsq_f32_e32 v143, v133
	s_waitcnt vmcnt(2)
	v_pk_fma_f32 v[132:133], v[244:245], s[86:87], v[136:137] op_sel_hi:[1,0,0]
	v_rsq_f32_e32 v145, v132
	v_rsq_f32_e32 v142, v133
	v_pk_fma_f32 v[132:133], v[246:247], s[86:87], v[136:137] op_sel_hi:[1,0,0]
	v_rsq_f32_e32 v140, v132
	v_rsq_f32_e32 v138, v133
	s_waitcnt vmcnt(1)
	v_pk_fma_f32 v[132:133], v[170:171], s[86:87], v[136:137] op_sel_hi:[1,0,0]
	v_rsq_f32_e32 v147, v132
	v_rsq_f32_e32 v144, v133
	v_pk_fma_f32 v[132:133], v[172:173], s[86:87], v[136:137] op_sel_hi:[1,0,0]
	v_rsq_f32_e32 v141, v132
	v_rsq_f32_e32 v139, v133
	s_waitcnt vmcnt(0)
; DI bf16_t to_bf16(float x) { return (bf16_t)(pack_bf16(x, 0.f) & 0xffffu); }
;   DI void run8(f32x4 (&acc)[8][4], int rb, int cb, int fr, int fq) const {
;     const int lane = fq * 16 + fr, wid = (int)(threadIdx.x >> 6);
;     bf16_t* scr = (bf16_t*)(smem + G8_STAGE_B + wid * 1280);
;     const int srow = lane >> 2, sch = lane & 3;
;     bf16_t* ap = act + (size_t)(rb + srow) * LDA + (cb >> 1) + sch * 8;
;     float rsv[8][4];
; #pragma unroll
;     for (int m = 0; m < 8; ++m)
; #pragma unroll
;       for (int j = 0; j < 4; ++j) rsv[m][j] = rsqrtf(ssq[rb + m * 16 + fq * 4 + j] * (1.f / D) + EPS);
; #pragma unroll
;     for (int m = 0; m < 8; ++m) {
; #pragma unroll
;       for (int j = 0; j < 4; ++j)
; #pragma unroll
;         for (int pi = 0; pi < 2; ++pi) {
;           const float g = acc[m][2 * pi][j] * rsv[m][j], u = acc[m][2 * pi + 1][j] * rsv[m][j];
;           const float a = g * __builtin_amdgcn_rcpf(1.f + __expf(-g)) * u;
;           scr[(fq * 4 + j) * 40 + pi * 16 + fr] = to_bf16(a);
;         }
;       __builtin_amdgcn_sched_barrier(0);
;       const u32x4 o = *(const u32x4*)(scr + srow * 40 + sch * 8);
;       *(u32x4*)(ap + (size_t)(m * 16) * LDA) = o;
;       __builtin_amdgcn_sched_barrier(0);
	v_pk_fma_f32 v[130:131], v[174:175], s[86:87], v[136:137] op_sel_hi:[1,0,0]
	v_rsq_f32_e32 v152, v130
	v_rsq_f32_e32 v149, v131
	v_pk_fma_f32 v[130:131], v[176:177], s[86:87], v[136:137] op_sel_hi:[1,0,0]
	v_rsq_f32_e32 v136, v130
	s_movk_i32 s0, 0x1680
	v_lshlrev_b32_e32 v132, 1, v223
	v_rsq_f32_e32 v133, v131
	v_mov_b64_e32 v[130:131], s[52:53]
	v_mad_i64_i32 v[130:131], s[0:1], v0, s0, v[130:131]
	v_lshlrev_b32_e32 v0, 4, v223
	v_lshl_add_u64 v[130:131], v[134:135], 1, v[130:131]
	v_and_b32_e32 v0, 48, v0
	v_mul_u32_u24_e32 v134, 0x50, v222
	v_lshl_add_u64 v[130:131], v[130:131], 0, v[0:1]
	v_add3_u32 v0, v217, v134, v0
	v_mul_u32_u24_e32 v134, 0x140, v168
	v_add3_u32 v132, v217, v132, v134
	v_mul_f32_e32 v134, 0xbfb8aa3b, v122
	v_exp_f32_e32 v134, v134
	s_nop 0
	v_add_f32_e32 v134, 1.0, v134
	v_rcp_f32_e32 v134, v134
	s_nop 0
	v_mul_f32_e32 v122, v122, v134
	v_mul_f32_e32 v122, v126, v122
	v_cvt_pk_bf16_f32 v122, v122, s0
	ds_write_b16 v132, v122
	v_mul_f32_e32 v122, 0xbfb8aa3b, v114
	v_exp_f32_e32 v122, v122
	s_nop 0
	v_add_f32_e32 v122, 1.0, v122
	v_rcp_f32_e32 v122, v122
	s_nop 0
	v_mul_f32_e32 v114, v114, v122
	v_mul_f32_e32 v114, v118, v114
	v_cvt_pk_bf16_f32 v114, v114, s0
	ds_write_b16 v132, v114 offset:32
	v_mul_f32_e32 v114, v123, v166
	v_mul_f32_e32 v122, 0xbfb8aa3b, v114
	v_exp_f32_e32 v122, v122
	v_mul_f32_e32 v118, v127, v166
	v_add_f32_e32 v122, 1.0, v122
	v_rcp_f32_e32 v122, v122
	s_nop 0
	v_mul_f32_e32 v114, v114, v122
	v_mul_f32_e32 v114, v118, v114
	v_cvt_pk_bf16_f32 v114, v114, s0
	ds_write_b16 v132, v114 offset:80
	v_mul_f32_e32 v114, v115, v166
	v_mul_f32_e32 v118, 0xbfb8aa3b, v114
	v_exp_f32_e32 v118, v118
	v_mul_f32_e32 v115, v119, v166
	v_add_f32_e32 v118, 1.0, v118
	v_rcp_f32_e32 v118, v118
	s_nop 0
	v_mul_f32_e32 v114, v114, v118
	v_mul_f32_e32 v114, v115, v114
	v_cvt_pk_bf16_f32 v114, v114, s0
	ds_write_b16 v132, v114 offset:112
	v_mul_f32_e32 v114, v124, v165
	v_mul_f32_e32 v118, 0xbfb8aa3b, v114
	v_exp_f32_e32 v118, v118
	v_mul_f32_e32 v115, v128, v165
	v_add_f32_e32 v118, 1.0, v118
	v_rcp_f32_e32 v118, v118
	s_nop 0
	v_mul_f32_e32 v114, v114, v118
	v_mul_f32_e32 v114, v115, v114
	v_cvt_pk_bf16_f32 v114, v114, s0
	ds_write_b16 v132, v114 offset:160
	v_mul_f32_e32 v114, v116, v165
	v_mul_f32_e32 v116, 0xbfb8aa3b, v114
	v_exp_f32_e32 v116, v116
	v_mul_f32_e32 v115, v120, v165
	v_add_f32_e32 v116, 1.0, v116
	v_rcp_f32_e32 v116, v116
	s_nop 0
	v_mul_f32_e32 v114, v114, v116
	v_mul_f32_e32 v114, v115, v114
	v_cvt_pk_bf16_f32 v114, v114, s0
	ds_write_b16 v132, v114 offset:192
	v_mul_f32_e32 v114, v125, v163
	v_mul_f32_e32 v116, 0xbfb8aa3b, v114
	v_exp_f32_e32 v116, v116
	v_mul_f32_e32 v115, v129, v163
	v_add_f32_e32 v116, 1.0, v116
	v_rcp_f32_e32 v116, v116
	s_nop 0
	v_mul_f32_e32 v114, v114, v116
	v_mul_f32_e32 v114, v115, v114
	v_cvt_pk_bf16_f32 v114, v114, s0
	ds_write_b16 v132, v114 offset:240
	v_mul_f32_e32 v114, v117, v163
	v_mul_f32_e32 v116, 0xbfb8aa3b, v114
	v_exp_f32_e32 v116, v116
	v_mul_f32_e32 v115, v121, v163
	v_add_f32_e32 v116, 1.0, v116
	v_rcp_f32_e32 v116, v116
	s_nop 0
	v_mul_f32_e32 v114, v114, v116
	v_mul_f32_e32 v114, v115, v114
	v_cvt_pk_bf16_f32 v114, v114, s0
	ds_write_b16 v132, v114 offset:272
	ds_read_b128 v[114:117], v0
	s_waitcnt lgkmcnt(0)
	global_store_dwordx4 v[130:131], v[114:117], off
	v_mul_f32_e32 v106, v106, v164
	s_nop 0
	v_mul_f32_e32 v114, 0xbfb8aa3b, v106
	v_exp_f32_e32 v114, v114
	v_mul_f32_e32 v110, v110, v164
	v_mul_f32_e32 v98, v98, v164
	v_mul_f32_e32 v102, v102, v164
	v_add_f32_e32 v114, 1.0, v114
	v_rcp_f32_e32 v114, v114
	s_nop 0
	v_mul_f32_e32 v106, v106, v114
	v_mul_f32_e32 v106, v110, v106
	v_cvt_pk_bf16_f32 v106, v106, s0
	ds_write_b16 v132, v106
	v_mul_f32_e32 v106, 0xbfb8aa3b, v98
	v_exp_f32_e32 v106, v106
	s_nop 0
	v_add_f32_e32 v106, 1.0, v106
	v_rcp_f32_e32 v106, v106
	s_nop 0
	v_mul_f32_e32 v98, v98, v106
	v_mul_f32_e32 v98, v102, v98
	v_cvt_pk_bf16_f32 v98, v98, s0
	ds_write_b16 v132, v98 offset:32
	v_mul_f32_e32 v98, v107, v162
	v_mul_f32_e32 v106, 0xbfb8aa3b, v98
	v_exp_f32_e32 v106, v106
	v_mul_f32_e32 v102, v111, v162
	v_add_f32_e32 v106, 1.0, v106
	v_rcp_f32_e32 v106, v106
	s_nop 0
	v_mul_f32_e32 v98, v98, v106
	v_mul_f32_e32 v98, v102, v98
	v_cvt_pk_bf16_f32 v98, v98, s0
	ds_write_b16 v132, v98 offset:80
	v_mul_f32_e32 v98, v99, v162
	v_mul_f32_e32 v102, 0xbfb8aa3b, v98
	v_exp_f32_e32 v102, v102
	v_mul_f32_e32 v99, v103, v162
	v_add_f32_e32 v102, 1.0, v102
	v_rcp_f32_e32 v102, v102
	s_nop 0
	v_mul_f32_e32 v98, v98, v102
	v_mul_f32_e32 v98, v99, v98
	v_cvt_pk_bf16_f32 v98, v98, s0
	ds_write_b16 v132, v98 offset:112
	v_mul_f32_e32 v98, v108, v161
	v_mul_f32_e32 v102, 0xbfb8aa3b, v98
	v_exp_f32_e32 v102, v102
	v_mul_f32_e32 v99, v112, v161
	v_add_f32_e32 v102, 1.0, v102
	v_rcp_f32_e32 v102, v102
	s_nop 0
	v_mul_f32_e32 v98, v98, v102
	v_mul_f32_e32 v98, v99, v98
	v_cvt_pk_bf16_f32 v98, v98, s0
	ds_write_b16 v132, v98 offset:160
	v_mul_f32_e32 v98, v100, v161
	v_mul_f32_e32 v100, 0xbfb8aa3b, v98
	v_exp_f32_e32 v100, v100
	v_mul_f32_e32 v99, v104, v161
	v_add_f32_e32 v100, 1.0, v100
	v_rcp_f32_e32 v100, v100
	s_nop 0
	v_mul_f32_e32 v98, v98, v100
	v_mul_f32_e32 v98, v99, v98
	v_cvt_pk_bf16_f32 v98, v98, s0
	ds_write_b16 v132, v98 offset:192
	v_mul_f32_e32 v98, v109, v159
	v_mul_f32_e32 v100, 0xbfb8aa3b, v98
	v_exp_f32_e32 v100, v100
	v_mul_f32_e32 v99, v113, v159
	v_add_f32_e32 v100, 1.0, v100
	v_rcp_f32_e32 v100, v100
	s_nop 0
	v_mul_f32_e32 v98, v98, v100
	v_mul_f32_e32 v98, v99, v98
	v_cvt_pk_bf16_f32 v98, v98, s0
	ds_write_b16 v132, v98 offset:240
	v_mul_f32_e32 v98, v101, v159
	v_mul_f32_e32 v100, 0xbfb8aa3b, v98
	v_exp_f32_e32 v100, v100
	v_mul_f32_e32 v99, v105, v159
	v_add_f32_e32 v100, 1.0, v100
	v_rcp_f32_e32 v100, v100
	s_nop 0
	v_mul_f32_e32 v98, v98, v100
	v_mul_f32_e32 v98, v99, v98
	v_cvt_pk_bf16_f32 v98, v98, s0
	ds_write_b16 v132, v98 offset:272
	ds_read_b128 v[98:101], v0
	s_mov_b32 s0, 0x16000
	v_add_co_u32_e32 v102, vcc, s0, v130
	s_nop 1
	v_addc_co_u32_e32 v103, vcc, 0, v131, vcc
	s_waitcnt lgkmcnt(0)
; DI bf16_t to_bf16(float x) { return (bf16_t)(pack_bf16(x, 0.f) & 0xffffu); }
;   DI void run8(f32x4 (&acc)[8][4], int rb, int cb, int fr, int fq) const {
;     ...
;     for (int m = 0; m < 8; ++m) {
; #pragma unroll
;       for (int j = 0; j < 4; ++j)
; #pragma unroll
;         for (int pi = 0; pi < 2; ++pi) {
;           const float g = acc[m][2 * pi][j] * rsv[m][j], u = acc[m][2 * pi + 1][j] * rsv[m][j];
;           const float a = g * __builtin_amdgcn_rcpf(1.f + __expf(-g)) * u;
;           scr[(fq * 4 + j) * 40 + pi * 16 + fr] = to_bf16(a);
;         }
;       __builtin_amdgcn_sched_barrier(0);
;       const u32x4 o = *(const u32x4*)(scr + srow * 40 + sch * 8);
;       *(u32x4*)(ap + (size_t)(m * 16) * LDA) = o;
;       __builtin_amdgcn_sched_barrier(0);
	global_store_dwordx4 v[102:103], v[98:101], off offset:2048
	v_mul_f32_e32 v90, v90, v160
	s_nop 0
	v_mul_f32_e32 v98, 0xbfb8aa3b, v90
	v_exp_f32_e32 v98, v98
	v_mul_f32_e32 v94, v94, v160
	v_mul_f32_e32 v82, v82, v160
	v_mul_f32_e32 v86, v86, v160
	v_add_f32_e32 v98, 1.0, v98
	v_rcp_f32_e32 v98, v98
	s_nop 0
	v_mul_f32_e32 v90, v90, v98
	v_mul_f32_e32 v90, v94, v90
	v_cvt_pk_bf16_f32 v90, v90, s0
	ds_write_b16 v132, v90
	v_mul_f32_e32 v90, 0xbfb8aa3b, v82
	v_exp_f32_e32 v90, v90
	s_nop 0
	v_add_f32_e32 v90, 1.0, v90
	v_rcp_f32_e32 v90, v90
	s_nop 0
	v_mul_f32_e32 v82, v82, v90
	v_mul_f32_e32 v82, v86, v82
	v_cvt_pk_bf16_f32 v82, v82, s0
	ds_write_b16 v132, v82 offset:32
	v_mul_f32_e32 v82, v91, v158
	v_mul_f32_e32 v90, 0xbfb8aa3b, v82
	v_exp_f32_e32 v90, v90
	v_mul_f32_e32 v86, v95, v158
	v_add_f32_e32 v90, 1.0, v90
	v_rcp_f32_e32 v90, v90
	s_nop 0
	v_mul_f32_e32 v82, v82, v90
	v_mul_f32_e32 v82, v86, v82
	v_cvt_pk_bf16_f32 v82, v82, s0
	ds_write_b16 v132, v82 offset:80
	v_mul_f32_e32 v82, v83, v158
	v_mul_f32_e32 v86, 0xbfb8aa3b, v82
	v_exp_f32_e32 v86, v86
	v_mul_f32_e32 v83, v87, v158
	v_add_f32_e32 v86, 1.0, v86
	v_rcp_f32_e32 v86, v86
	s_nop 0
	v_mul_f32_e32 v82, v82, v86
	v_mul_f32_e32 v82, v83, v82
	v_cvt_pk_bf16_f32 v82, v82, s0
	ds_write_b16 v132, v82 offset:112
	v_mul_f32_e32 v82, v92, v157
	v_mul_f32_e32 v86, 0xbfb8aa3b, v82
	v_exp_f32_e32 v86, v86
	v_mul_f32_e32 v83, v96, v157
	v_add_f32_e32 v86, 1.0, v86
	v_rcp_f32_e32 v86, v86
	s_nop 0
	v_mul_f32_e32 v82, v82, v86
	v_mul_f32_e32 v82, v83, v82
	v_cvt_pk_bf16_f32 v82, v82, s0
	ds_write_b16 v132, v82 offset:160
	v_mul_f32_e32 v82, v84, v157
	v_mul_f32_e32 v84, 0xbfb8aa3b, v82
	v_exp_f32_e32 v84, v84
	v_mul_f32_e32 v83, v88, v157
	v_add_f32_e32 v84, 1.0, v84
	v_rcp_f32_e32 v84, v84
	s_nop 0
	v_mul_f32_e32 v82, v82, v84
	v_mul_f32_e32 v82, v83, v82
	v_cvt_pk_bf16_f32 v82, v82, s0
	ds_write_b16 v132, v82 offset:192
	v_mul_f32_e32 v82, v93, v155
	v_mul_f32_e32 v84, 0xbfb8aa3b, v82
	v_exp_f32_e32 v84, v84
	v_mul_f32_e32 v83, v97, v155
	v_add_f32_e32 v84, 1.0, v84
	v_rcp_f32_e32 v84, v84
	s_nop 0
	v_mul_f32_e32 v82, v82, v84
	v_mul_f32_e32 v82, v83, v82
	v_cvt_pk_bf16_f32 v82, v82, s0
	ds_write_b16 v132, v82 offset:240
	v_mul_f32_e32 v82, v85, v155
	v_mul_f32_e32 v84, 0xbfb8aa3b, v82
	v_exp_f32_e32 v84, v84
	v_mul_f32_e32 v83, v89, v155
	v_add_f32_e32 v84, 1.0, v84
	v_rcp_f32_e32 v84, v84
	s_nop 0
	v_mul_f32_e32 v82, v82, v84
	v_mul_f32_e32 v82, v83, v82
	v_cvt_pk_bf16_f32 v82, v82, s0
	ds_write_b16 v132, v82 offset:272
	ds_read_b128 v[82:85], v0
	s_mov_b32 s0, 0x2d000
	v_add_co_u32_e32 v86, vcc, s0, v130
	s_nop 1
	v_addc_co_u32_e32 v87, vcc, 0, v131, vcc
	s_waitcnt lgkmcnt(0)
	global_store_dwordx4 v[86:87], v[82:85], off
	v_mul_f32_e32 v74, v74, v156
	s_nop 0
	v_mul_f32_e32 v82, 0xbfb8aa3b, v74
	v_exp_f32_e32 v82, v82
	v_mul_f32_e32 v78, v78, v156
	v_mul_f32_e32 v66, v66, v156
	v_mul_f32_e32 v70, v70, v156
	v_add_f32_e32 v82, 1.0, v82
	v_rcp_f32_e32 v82, v82
	s_nop 0
	v_mul_f32_e32 v74, v74, v82
	v_mul_f32_e32 v74, v78, v74
	v_cvt_pk_bf16_f32 v74, v74, s0
	ds_write_b16 v132, v74
	v_mul_f32_e32 v74, 0xbfb8aa3b, v66
	v_exp_f32_e32 v74, v74
	s_nop 0
	v_add_f32_e32 v74, 1.0, v74
	v_rcp_f32_e32 v74, v74
	s_nop 0
	v_mul_f32_e32 v66, v66, v74
	v_mul_f32_e32 v66, v70, v66
	v_cvt_pk_bf16_f32 v66, v66, s0
	ds_write_b16 v132, v66 offset:32
	v_mul_f32_e32 v66, v75, v154
	v_mul_f32_e32 v74, 0xbfb8aa3b, v66
	v_exp_f32_e32 v74, v74
	v_mul_f32_e32 v70, v79, v154
	v_add_f32_e32 v74, 1.0, v74
	v_rcp_f32_e32 v74, v74
	s_nop 0
	v_mul_f32_e32 v66, v66, v74
	v_mul_f32_e32 v66, v70, v66
	v_cvt_pk_bf16_f32 v66, v66, s0
	ds_write_b16 v132, v66 offset:80
	v_mul_f32_e32 v66, v67, v154
	v_mul_f32_e32 v70, 0xbfb8aa3b, v66
	v_exp_f32_e32 v70, v70
	v_mul_f32_e32 v67, v71, v154
	v_add_f32_e32 v70, 1.0, v70
	v_rcp_f32_e32 v70, v70
	s_nop 0
	v_mul_f32_e32 v66, v66, v70
	v_mul_f32_e32 v66, v67, v66
	v_cvt_pk_bf16_f32 v66, v66, s0
	ds_write_b16 v132, v66 offset:112
	v_mul_f32_e32 v66, v76, v153
	v_mul_f32_e32 v70, 0xbfb8aa3b, v66
	v_exp_f32_e32 v70, v70
	v_mul_f32_e32 v67, v80, v153
	v_add_f32_e32 v70, 1.0, v70
	v_rcp_f32_e32 v70, v70
	s_nop 0
	v_mul_f32_e32 v66, v66, v70
	v_mul_f32_e32 v66, v67, v66
	v_cvt_pk_bf16_f32 v66, v66, s0
	ds_write_b16 v132, v66 offset:160
	v_mul_f32_e32 v66, v68, v153
	v_mul_f32_e32 v68, 0xbfb8aa3b, v66
	v_exp_f32_e32 v68, v68
	v_mul_f32_e32 v67, v72, v153
	v_add_f32_e32 v68, 1.0, v68
	v_rcp_f32_e32 v68, v68
	s_nop 0
	v_mul_f32_e32 v66, v66, v68
	v_mul_f32_e32 v66, v67, v66
	v_cvt_pk_bf16_f32 v66, v66, s0
	ds_write_b16 v132, v66 offset:192
	v_mul_f32_e32 v66, v77, v150
	v_mul_f32_e32 v68, 0xbfb8aa3b, v66
	v_exp_f32_e32 v68, v68
	v_mul_f32_e32 v67, v81, v150
	v_add_f32_e32 v68, 1.0, v68
	v_rcp_f32_e32 v68, v68
	s_nop 0
	v_mul_f32_e32 v66, v66, v68
	v_mul_f32_e32 v66, v67, v66
	v_cvt_pk_bf16_f32 v66, v66, s0
	ds_write_b16 v132, v66 offset:240
	v_mul_f32_e32 v66, v69, v150
	v_mul_f32_e32 v68, 0xbfb8aa3b, v66
	v_exp_f32_e32 v68, v68
	v_mul_f32_e32 v67, v73, v150
	v_add_f32_e32 v68, 1.0, v68
	v_rcp_f32_e32 v68, v68
	s_nop 0
	v_mul_f32_e32 v66, v66, v68
	v_mul_f32_e32 v66, v67, v66
	v_cvt_pk_bf16_f32 v66, v66, s0
	ds_write_b16 v132, v66 offset:272
	ds_read_b128 v[66:69], v0
	s_mov_b32 s0, 0x43000
	v_add_co_u32_e32 v70, vcc, s0, v130
	s_nop 1
	v_addc_co_u32_e32 v71, vcc, 0, v131, vcc
	s_waitcnt lgkmcnt(0)
; DI bf16_t to_bf16(float x) { return (bf16_t)(pack_bf16(x, 0.f) & 0xffffu); }
;   DI void run8(f32x4 (&acc)[8][4], int rb, int cb, int fr, int fq) const {
;     ...
;     for (int m = 0; m < 8; ++m) {
; #pragma unroll
;       for (int j = 0; j < 4; ++j)
; #pragma unroll
;         for (int pi = 0; pi < 2; ++pi) {
;           const float g = acc[m][2 * pi][j] * rsv[m][j], u = acc[m][2 * pi + 1][j] * rsv[m][j];
;           const float a = g * __builtin_amdgcn_rcpf(1.f + __expf(-g)) * u;
;           scr[(fq * 4 + j) * 40 + pi * 16 + fr] = to_bf16(a);
;         }
;       __builtin_amdgcn_sched_barrier(0);
;       const u32x4 o = *(const u32x4*)(scr + srow * 40 + sch * 8);
;       *(u32x4*)(ap + (size_t)(m * 16) * LDA) = o;
;       __builtin_amdgcn_sched_barrier(0);
	global_store_dwordx4 v[70:71], v[66:69], off offset:2048
	v_mul_f32_e32 v58, v58, v151
	s_nop 0
	v_mul_f32_e32 v66, 0xbfb8aa3b, v58
	v_exp_f32_e32 v66, v66
	v_mul_f32_e32 v62, v62, v151
	v_mul_f32_e32 v50, v50, v151
	v_mul_f32_e32 v54, v54, v151
	v_add_f32_e32 v66, 1.0, v66
	v_rcp_f32_e32 v66, v66
	s_nop 0
	v_mul_f32_e32 v58, v58, v66
	v_mul_f32_e32 v58, v62, v58
	v_cvt_pk_bf16_f32 v58, v58, s0
	ds_write_b16 v132, v58
	v_mul_f32_e32 v58, 0xbfb8aa3b, v50
	v_exp_f32_e32 v58, v58
	s_nop 0
	v_add_f32_e32 v58, 1.0, v58
	v_rcp_f32_e32 v58, v58
	s_nop 0
	v_mul_f32_e32 v50, v50, v58
	v_mul_f32_e32 v50, v54, v50
	v_cvt_pk_bf16_f32 v50, v50, s0
	ds_write_b16 v132, v50 offset:32
	v_mul_f32_e32 v50, v59, v148
	v_mul_f32_e32 v58, 0xbfb8aa3b, v50
	v_exp_f32_e32 v58, v58
	v_mul_f32_e32 v54, v63, v148
	v_add_f32_e32 v58, 1.0, v58
	v_rcp_f32_e32 v58, v58
	s_nop 0
	v_mul_f32_e32 v50, v50, v58
	v_mul_f32_e32 v50, v54, v50
	v_cvt_pk_bf16_f32 v50, v50, s0
	ds_write_b16 v132, v50 offset:80
	v_mul_f32_e32 v50, v51, v148
	v_mul_f32_e32 v54, 0xbfb8aa3b, v50
	v_exp_f32_e32 v54, v54
	v_mul_f32_e32 v51, v55, v148
	v_add_f32_e32 v54, 1.0, v54
	v_rcp_f32_e32 v54, v54
	s_nop 0
	v_mul_f32_e32 v50, v50, v54
	v_mul_f32_e32 v50, v51, v50
	v_cvt_pk_bf16_f32 v50, v50, s0
	ds_write_b16 v132, v50 offset:112
	v_mul_f32_e32 v50, v60, v146
	v_mul_f32_e32 v54, 0xbfb8aa3b, v50
	v_exp_f32_e32 v54, v54
	v_mul_f32_e32 v51, v64, v146
	v_add_f32_e32 v54, 1.0, v54
	v_rcp_f32_e32 v54, v54
	s_nop 0
	v_mul_f32_e32 v50, v50, v54
	v_mul_f32_e32 v50, v51, v50
	v_cvt_pk_bf16_f32 v50, v50, s0
	ds_write_b16 v132, v50 offset:160
	v_mul_f32_e32 v50, v52, v146
	v_mul_f32_e32 v52, 0xbfb8aa3b, v50
	v_exp_f32_e32 v52, v52
	v_mul_f32_e32 v51, v56, v146
	v_add_f32_e32 v52, 1.0, v52
	v_rcp_f32_e32 v52, v52
	s_nop 0
	v_mul_f32_e32 v50, v50, v52
	v_mul_f32_e32 v50, v51, v50
	v_cvt_pk_bf16_f32 v50, v50, s0
	ds_write_b16 v132, v50 offset:192
	v_mul_f32_e32 v50, v61, v143
	v_mul_f32_e32 v52, 0xbfb8aa3b, v50
	v_exp_f32_e32 v52, v52
	v_mul_f32_e32 v51, v65, v143
	v_add_f32_e32 v52, 1.0, v52
	v_rcp_f32_e32 v52, v52
	s_nop 0
	v_mul_f32_e32 v50, v50, v52
	v_mul_f32_e32 v50, v51, v50
	v_cvt_pk_bf16_f32 v50, v50, s0
	ds_write_b16 v132, v50 offset:240
	v_mul_f32_e32 v50, v53, v143
	v_mul_f32_e32 v52, 0xbfb8aa3b, v50
	v_exp_f32_e32 v52, v52
	v_mul_f32_e32 v51, v57, v143
	v_add_f32_e32 v52, 1.0, v52
	v_rcp_f32_e32 v52, v52
	s_nop 0
	v_mul_f32_e32 v50, v50, v52
	v_mul_f32_e32 v50, v51, v50
	v_cvt_pk_bf16_f32 v50, v50, s0
	ds_write_b16 v132, v50 offset:272
	ds_read_b128 v[50:53], v0
	s_mov_b32 s0, 0x5a000
	v_add_co_u32_e32 v54, vcc, s0, v130
	s_nop 1
	v_addc_co_u32_e32 v55, vcc, 0, v131, vcc
	s_waitcnt lgkmcnt(0)
	global_store_dwordx4 v[54:55], v[50:53], off
	v_mul_f32_e32 v42, v42, v145
	s_nop 0
	v_mul_f32_e32 v50, 0xbfb8aa3b, v42
	v_exp_f32_e32 v50, v50
	v_mul_f32_e32 v46, v46, v145
	v_mul_f32_e32 v34, v34, v145
	v_mul_f32_e32 v38, v38, v145
	v_add_f32_e32 v50, 1.0, v50
	v_rcp_f32_e32 v50, v50
	s_nop 0
	v_mul_f32_e32 v42, v42, v50
	v_mul_f32_e32 v42, v46, v42
	v_cvt_pk_bf16_f32 v42, v42, s0
	ds_write_b16 v132, v42
	v_mul_f32_e32 v42, 0xbfb8aa3b, v34
	v_exp_f32_e32 v42, v42
	s_nop 0
	v_add_f32_e32 v42, 1.0, v42
	v_rcp_f32_e32 v42, v42
	s_nop 0
	v_mul_f32_e32 v34, v34, v42
	v_mul_f32_e32 v34, v38, v34
	v_cvt_pk_bf16_f32 v34, v34, s0
	ds_write_b16 v132, v34 offset:32
	v_mul_f32_e32 v34, v43, v142
	v_mul_f32_e32 v42, 0xbfb8aa3b, v34
	v_exp_f32_e32 v42, v42
	v_mul_f32_e32 v38, v47, v142
	v_add_f32_e32 v42, 1.0, v42
	v_rcp_f32_e32 v42, v42
	s_nop 0
	v_mul_f32_e32 v34, v34, v42
	v_mul_f32_e32 v34, v38, v34
	v_cvt_pk_bf16_f32 v34, v34, s0
	ds_write_b16 v132, v34 offset:80
	v_mul_f32_e32 v34, v35, v142
	v_mul_f32_e32 v38, 0xbfb8aa3b, v34
	v_exp_f32_e32 v38, v38
	v_mul_f32_e32 v35, v39, v142
	v_add_f32_e32 v38, 1.0, v38
	v_rcp_f32_e32 v38, v38
	s_nop 0
	v_mul_f32_e32 v34, v34, v38
	v_mul_f32_e32 v34, v35, v34
	v_cvt_pk_bf16_f32 v34, v34, s0
	ds_write_b16 v132, v34 offset:112
	v_mul_f32_e32 v34, v44, v140
	v_mul_f32_e32 v38, 0xbfb8aa3b, v34
	v_exp_f32_e32 v38, v38
	v_mul_f32_e32 v35, v48, v140
	v_add_f32_e32 v38, 1.0, v38
	v_rcp_f32_e32 v38, v38
	s_nop 0
	v_mul_f32_e32 v34, v34, v38
	v_mul_f32_e32 v34, v35, v34
	v_cvt_pk_bf16_f32 v34, v34, s0
	ds_write_b16 v132, v34 offset:160
	v_mul_f32_e32 v34, v36, v140
	v_mul_f32_e32 v36, 0xbfb8aa3b, v34
	v_exp_f32_e32 v36, v36
	v_mul_f32_e32 v35, v40, v140
	v_add_f32_e32 v36, 1.0, v36
	v_rcp_f32_e32 v36, v36
	s_nop 0
	v_mul_f32_e32 v34, v34, v36
	v_mul_f32_e32 v34, v35, v34
	v_cvt_pk_bf16_f32 v34, v34, s0
	ds_write_b16 v132, v34 offset:192
	v_mul_f32_e32 v34, v45, v138
	v_mul_f32_e32 v36, 0xbfb8aa3b, v34
	v_exp_f32_e32 v36, v36
	v_mul_f32_e32 v35, v49, v138
	v_add_f32_e32 v36, 1.0, v36
	v_rcp_f32_e32 v36, v36
	s_nop 0
	v_mul_f32_e32 v34, v34, v36
	v_mul_f32_e32 v34, v35, v34
	v_cvt_pk_bf16_f32 v34, v34, s0
	ds_write_b16 v132, v34 offset:240
	v_mul_f32_e32 v34, v37, v138
	v_mul_f32_e32 v36, 0xbfb8aa3b, v34
	v_exp_f32_e32 v36, v36
	v_mul_f32_e32 v35, v41, v138
	v_add_f32_e32 v36, 1.0, v36
	v_rcp_f32_e32 v36, v36
	s_nop 0
	v_mul_f32_e32 v34, v34, v36
	v_mul_f32_e32 v34, v35, v34
	v_cvt_pk_bf16_f32 v34, v34, s0
	ds_write_b16 v132, v34 offset:272
	ds_read_b128 v[34:37], v0
	v_add_co_u32_e32 v38, vcc, s68, v130
	s_nop 1
	v_addc_co_u32_e32 v39, vcc, 0, v131, vcc
	s_waitcnt lgkmcnt(0)
; DI bf16_t to_bf16(float x) { return (bf16_t)(pack_bf16(x, 0.f) & 0xffffu); }
; template <class Epi>
; DI void gemm8_tile(const bf16_t* __restrict__ Ab, int lda, const bf16_t* __restrict__ Bb, int ldb, int K, int brow, int bcol, const Epi epi,
;                    bool staged, bool has_next, const bf16_t* __restrict__ Abn, const bf16_t* __restrict__ Bbn) {
;     ...
;   if (Epi::LDS_SCRATCH) __syncthreads();
;   DI void run8(f32x4 (&acc)[8][4], int rb, int cb, int fr, int fq) const {
;     ...
;     for (int m = 0; m < 8; ++m) {
; #pragma unroll
;       for (int j = 0; j < 4; ++j)
; #pragma unroll
;         for (int pi = 0; pi < 2; ++pi) {
;           const float g = acc[m][2 * pi][j] * rsv[m][j], u = acc[m][2 * pi + 1][j] * rsv[m][j];
;           const float a = g * __builtin_amdgcn_rcpf(1.f + __expf(-g)) * u;
;           scr[(fq * 4 + j) * 40 + pi * 16 + fr] = to_bf16(a);
;         }
;       __builtin_amdgcn_sched_barrier(0);
;       const u32x4 o = *(const u32x4*)(scr + srow * 40 + sch * 8);
;       *(u32x4*)(ap + (size_t)(m * 16) * LDA) = o;
;       __builtin_amdgcn_sched_barrier(0);
	global_store_dwordx4 v[38:39], v[34:37], off offset:2048
	v_mul_f32_e32 v26, v26, v147
	s_nop 0
	v_mul_f32_e32 v34, 0xbfb8aa3b, v26
	v_exp_f32_e32 v34, v34
	v_mul_f32_e32 v30, v30, v147
	v_mul_f32_e32 v18, v18, v147
	v_mul_f32_e32 v22, v22, v147
	v_add_f32_e32 v34, 1.0, v34
	v_rcp_f32_e32 v34, v34
	s_nop 0
	v_mul_f32_e32 v26, v26, v34
	v_mul_f32_e32 v26, v30, v26
	v_cvt_pk_bf16_f32 v26, v26, s0
	ds_write_b16 v132, v26
	v_mul_f32_e32 v26, 0xbfb8aa3b, v18
	v_exp_f32_e32 v26, v26
	s_nop 0
	v_add_f32_e32 v26, 1.0, v26
	v_rcp_f32_e32 v26, v26
	s_nop 0
	v_mul_f32_e32 v18, v18, v26
	v_mul_f32_e32 v18, v22, v18
	v_cvt_pk_bf16_f32 v18, v18, s0
	ds_write_b16 v132, v18 offset:32
	v_mul_f32_e32 v18, v27, v144
	v_mul_f32_e32 v26, 0xbfb8aa3b, v18
	v_exp_f32_e32 v26, v26
	v_mul_f32_e32 v22, v31, v144
	v_add_f32_e32 v26, 1.0, v26
	v_rcp_f32_e32 v26, v26
	s_nop 0
	v_mul_f32_e32 v18, v18, v26
	v_mul_f32_e32 v18, v22, v18
	v_cvt_pk_bf16_f32 v18, v18, s0
	ds_write_b16 v132, v18 offset:80
	v_mul_f32_e32 v18, v19, v144
	v_mul_f32_e32 v22, 0xbfb8aa3b, v18
	v_exp_f32_e32 v22, v22
	v_mul_f32_e32 v19, v23, v144
	v_add_f32_e32 v22, 1.0, v22
	v_rcp_f32_e32 v22, v22
	s_nop 0
	v_mul_f32_e32 v18, v18, v22
	v_mul_f32_e32 v18, v19, v18
	v_cvt_pk_bf16_f32 v18, v18, s0
	ds_write_b16 v132, v18 offset:112
	v_mul_f32_e32 v18, v28, v141
	v_mul_f32_e32 v22, 0xbfb8aa3b, v18
	v_exp_f32_e32 v22, v22
	v_mul_f32_e32 v19, v32, v141
	v_add_f32_e32 v22, 1.0, v22
	v_rcp_f32_e32 v22, v22
	s_nop 0
	v_mul_f32_e32 v18, v18, v22
	v_mul_f32_e32 v18, v19, v18
	v_cvt_pk_bf16_f32 v18, v18, s0
	ds_write_b16 v132, v18 offset:160
	v_mul_f32_e32 v18, v20, v141
	v_mul_f32_e32 v20, 0xbfb8aa3b, v18
	v_exp_f32_e32 v20, v20
	v_mul_f32_e32 v19, v24, v141
	v_add_f32_e32 v20, 1.0, v20
	v_rcp_f32_e32 v20, v20
	s_nop 0
	v_mul_f32_e32 v18, v18, v20
	v_mul_f32_e32 v18, v19, v18
	v_cvt_pk_bf16_f32 v18, v18, s0
	ds_write_b16 v132, v18 offset:192
	v_mul_f32_e32 v18, v29, v139
	v_mul_f32_e32 v20, 0xbfb8aa3b, v18
	v_exp_f32_e32 v20, v20
	v_mul_f32_e32 v19, v33, v139
	v_add_f32_e32 v20, 1.0, v20
	v_rcp_f32_e32 v20, v20
	s_nop 0
	v_mul_f32_e32 v18, v18, v20
	v_mul_f32_e32 v18, v19, v18
	v_cvt_pk_bf16_f32 v18, v18, s0
	ds_write_b16 v132, v18 offset:240
	v_mul_f32_e32 v18, v21, v139
	v_mul_f32_e32 v20, 0xbfb8aa3b, v18
	v_exp_f32_e32 v20, v20
	v_mul_f32_e32 v19, v25, v139
	v_add_f32_e32 v20, 1.0, v20
	v_rcp_f32_e32 v20, v20
	s_nop 0
	v_mul_f32_e32 v18, v18, v20
	v_mul_f32_e32 v18, v19, v18
	v_cvt_pk_bf16_f32 v18, v18, s0
	ds_write_b16 v132, v18 offset:272
	ds_read_b128 v[18:21], v0
	s_mov_b32 s0, 0x87000
	v_add_co_u32_e32 v22, vcc, s0, v130
	s_nop 1
	v_addc_co_u32_e32 v23, vcc, 0, v131, vcc
	s_waitcnt lgkmcnt(0)
	global_store_dwordx4 v[22:23], v[18:21], off
	v_mul_f32_e32 v10, v10, v152
	s_nop 0
	v_mul_f32_e32 v18, 0xbfb8aa3b, v10
	v_exp_f32_e32 v18, v18
	v_mul_f32_e32 v14, v14, v152
	v_mul_f32_e32 v2, v2, v152
	v_mul_f32_e32 v6, v6, v152
	v_add_f32_e32 v18, 1.0, v18
	v_rcp_f32_e32 v18, v18
	s_nop 0
	v_mul_f32_e32 v10, v10, v18
	v_mul_f32_e32 v10, v14, v10
	v_cvt_pk_bf16_f32 v10, v10, s0
	ds_write_b16 v132, v10
	v_mul_f32_e32 v10, 0xbfb8aa3b, v2
	v_exp_f32_e32 v10, v10
	s_nop 0
	v_add_f32_e32 v10, 1.0, v10
	v_rcp_f32_e32 v10, v10
	s_nop 0
	v_mul_f32_e32 v2, v2, v10
	v_mul_f32_e32 v2, v6, v2
	v_cvt_pk_bf16_f32 v2, v2, s0
	ds_write_b16 v132, v2 offset:32
	v_mul_f32_e32 v2, v11, v149
	v_mul_f32_e32 v10, 0xbfb8aa3b, v2
	v_exp_f32_e32 v10, v10
	v_mul_f32_e32 v6, v15, v149
	v_add_f32_e32 v10, 1.0, v10
	v_rcp_f32_e32 v10, v10
	s_nop 0
	v_mul_f32_e32 v2, v2, v10
	v_mul_f32_e32 v2, v6, v2
	v_cvt_pk_bf16_f32 v2, v2, s0
	ds_write_b16 v132, v2 offset:80
	v_mul_f32_e32 v2, v3, v149
	v_mul_f32_e32 v6, 0xbfb8aa3b, v2
	v_exp_f32_e32 v6, v6
	v_mul_f32_e32 v3, v7, v149
	v_add_f32_e32 v6, 1.0, v6
	v_rcp_f32_e32 v6, v6
	s_nop 0
	v_mul_f32_e32 v2, v2, v6
	v_mul_f32_e32 v2, v3, v2
	v_cvt_pk_bf16_f32 v2, v2, s0
	ds_write_b16 v132, v2 offset:112
	v_mul_f32_e32 v2, v12, v136
	v_mul_f32_e32 v6, 0xbfb8aa3b, v2
	v_exp_f32_e32 v6, v6
	v_mul_f32_e32 v3, v16, v136
	v_add_f32_e32 v6, 1.0, v6
	v_rcp_f32_e32 v6, v6
	s_nop 0
	v_mul_f32_e32 v2, v2, v6
	v_mul_f32_e32 v2, v3, v2
	v_cvt_pk_bf16_f32 v2, v2, s0
	ds_write_b16 v132, v2 offset:160
	v_mul_f32_e32 v2, v4, v136
	v_mul_f32_e32 v4, 0xbfb8aa3b, v2
	v_exp_f32_e32 v4, v4
	v_mul_f32_e32 v3, v8, v136
	v_add_f32_e32 v4, 1.0, v4
	v_rcp_f32_e32 v4, v4
	s_nop 0
	v_mul_f32_e32 v2, v2, v4
	v_mul_f32_e32 v2, v3, v2
	v_cvt_pk_bf16_f32 v2, v2, s0
	ds_write_b16 v132, v2 offset:192
	v_mul_f32_e32 v2, v13, v133
	v_mul_f32_e32 v4, 0xbfb8aa3b, v2
	v_exp_f32_e32 v4, v4
	v_mul_f32_e32 v3, v17, v133
	v_add_f32_e32 v4, 1.0, v4
	v_rcp_f32_e32 v4, v4
	s_nop 0
	v_mul_f32_e32 v2, v2, v4
	v_mul_f32_e32 v2, v3, v2
	v_cvt_pk_bf16_f32 v2, v2, s0
	ds_write_b16 v132, v2 offset:240
	v_mul_f32_e32 v2, v5, v133
	v_mul_f32_e32 v4, 0xbfb8aa3b, v2
	v_exp_f32_e32 v4, v4
	v_mul_f32_e32 v3, v9, v133
	v_add_f32_e32 v4, 1.0, v4
	v_rcp_f32_e32 v4, v4
	s_nop 0
	v_mul_f32_e32 v2, v2, v4
	v_mul_f32_e32 v2, v3, v2
	v_cvt_pk_bf16_f32 v2, v2, s0
	ds_write_b16 v132, v2 offset:272
	ds_read_b128 v[2:5], v0
	v_add_co_u32_e32 v6, vcc, 0x9d000, v130
	s_nop 1
	v_addc_co_u32_e32 v7, vcc, 0, v131, vcc
	s_waitcnt lgkmcnt(0)
	global_store_dwordx4 v[6:7], v[2:5], off offset:2048
	s_andn2_b64 vcc, exec, s[6:7]
	s_mov_b64 s[0:1], -1
	s_barrier
	s_cbranch_vccz .LBB0_1678
